# P1 q/k-norm epilogue: the 16-lane row sums use DPP moves (quad_perm / row_half_mirror / row_mirror, same pairing as the xor butterfly) instead of 128 ds_bpermute round trips per tile
# speedup vs baseline: 1.0503x; 1.0028x over previous
; __device__ __forceinline__ void inproj_tile(const Params& p, char* smem, int l, int mt, int nt) {
;     ...
;       const bool isq = nt < 4;
;       const float* nw = (isq ? p.q_norm_w : p.k_norm_w) + l * 64;
;       float w4[4];
; #pragma unroll
;       for (int n = 0; n < 4; ++n) w4[n] = nw[n * 16 + fr] * (isq ? 0.125f : 1.f);
; #pragma unroll
;       for (int m = 0; m < 8; ++m)
; #pragma unroll
;         for (int j = 0; j < 4; ++j) {
;           float ss = 0.f;
; #pragma unroll
;           for (int n = 0; n < 4; ++n) ss += acc[m][n][j] * acc[m][n][j];
;           ss += __shfl_xor(ss, 1); ss += __shfl_xor(ss, 2); ss += __shfl_xor(ss, 4); ss += __shfl_xor(ss, 8);
;           float rstd = rsqrtf(ss * (1.f / 64.f) + EPSF);
;           int row = rowbase + m * 16 + fq * 4 + j;
;           float v[4];
; #pragma unroll
;           for (int n = 0; n < 4; ++n) v[n] = acc[m][n][j] * rstd * w4[n];
;           bool lat = row < MLAT;
;           float rv[4] = {v[0], v[1], v[2], v[3]};
;           if (lat) {
;             int t = row & 8191, pr = t >> 6, pc = t & 63;
;             float c0 = rope[pr * 16 + fr], s0 = rope[2048 + pr * 16 + fr];
;             float c1 = rope[pc * 16 + fr], s1 = rope[2048 + pc * 16 + fr];
;             rv[0] = v[0] * c0 - v[1] * s0; rv[1] = v[1] * c0 + v[0] * s0;
;             rv[2] = v[2] * c1 - v[3] * s1; rv[3] = v[3] * c1 + v[2] * s1;
;           }
.LBB0_309:
	s_andn2_b64 vcc, exec, s[0:1]
	s_cbranch_vccnz .LBB0_294
	s_add_u32 s6, s8, 0x18e24000
	s_addc_u32 s7, s9, 0
	s_cmp_gt_i32 s13, 3
	s_cselect_b64 s[10:11], -1, 0
	s_cmp_lt_i32 s13, 4
	s_cselect_b64 vcc, -1, 0
	s_and_b64 s[0:1], vcc, exec
	s_cselect_b32 s13, s81, s83
	s_cselect_b32 s14, s80, s82
	s_lshl_b32 s0, s12, 6
	s_ashr_i32 s1, s0, 31
	s_lshl_b64 s[0:1], s[0:1], 2
	s_add_u32 s0, s14, s0
	s_addc_u32 s1, s13, s1
	v_lshlrev_b32_e32 v135, 2, v168
	global_load_dword v136, v135, s[0:1]
	global_load_dword v137, v135, s[0:1] offset:64
	global_load_dword v145, v135, s[0:1] offset:128
	global_load_dword v144, v135, s[0:1] offset:192
	v_and_b32_e32 v141, 64, v173
	v_mov_b32_e32 v2, v120
	v_mov_b32_e32 v3, v124
	v_xor_b32_e32 v133, 1, v173
	v_mov_b32_e32 v138, v128
	v_mov_b32_e32 v139, v116
	v_add_u32_e32 v116, 64, v141
	v_pk_mul_f32 v[2:3], v[2:3], v[2:3]
	v_cndmask_b32_e32 v134, 1.0, v202, vcc
	v_pk_mul_f32 v[142:143], v[138:139], v[138:139]
	v_cmp_lt_i32_e32 vcc, v133, v116
	v_add_f32_e32 v2, v2, v3
	v_add_f32_e32 v2, v143, v2
	v_cndmask_b32_e32 v128, v173, v133, vcc
	v_lshlrev_b32_e32 v158, 2, v128
	v_add_f32_e32 v2, v142, v2
	s_nop 1
	v_mov_b32_dpp v3, v2 quad_perm:[1,0,3,2] row_mask:0xf bank_mask:0xf
	v_xor_b32_e32 v146, 2, v173
	v_cmp_lt_i32_e32 vcc, v146, v116
	v_xor_b32_e32 v128, 4, v173
	s_movk_i32 s0, 0x7e0
	v_cndmask_b32_e32 v133, v173, v146, vcc
	v_lshlrev_b32_e32 v159, 2, v133
	s_waitcnt lgkmcnt(0)
	v_add_f32_e32 v2, v2, v3
	s_nop 1
	v_mov_b32_dpp v3, v2 quad_perm:[2,3,0,1] row_mask:0xf bank_mask:0xf
	v_cmp_lt_i32_e32 vcc, v128, v116
	v_xor_b32_e32 v133, 8, v173
	s_waitcnt lgkmcnt(0)
	v_add_f32_e32 v3, v2, v3
	v_cndmask_b32_e32 v128, v173, v128, vcc
	v_lshlrev_b32_e32 v160, 2, v128
	s_nop 1
	v_mov_b32_dpp v128, v3 row_half_mirror row_mask:0xf bank_mask:0xf
	v_cmp_lt_i32_e32 vcc, v133, v116
	v_lshl_or_b32 v2, v140, 2, v132
	v_lshl_or_b32 v140, v140, 8, v135
	v_cndmask_b32_e32 v116, v173, v133, vcc
	v_lshlrev_b32_e32 v161, 2, v116
	s_waitcnt lgkmcnt(0)
	v_add_f32_e32 v3, v3, v128
	s_nop 1
	v_mov_b32_dpp v116, v3 row_mirror row_mask:0xf bank_mask:0xf
	v_lshrrev_b32_e32 v128, 2, v132
	v_mov_b32_e32 v132, v124
	v_mov_b32_e32 v133, v120
	v_and_or_b32 v120, v128, s0, v168
	s_waitcnt lgkmcnt(0)
	v_add_f32_e32 v3, v3, v116
	v_fmamk_f32 v3, v3, 0x3c800000, v197
	v_mul_f32_e32 v116, 0x4b800000, v3
	v_cmp_gt_f32_e32 vcc, s92, v3
	v_cmp_gt_i32_e64 s[0:1], s91, v2
	v_lshlrev_b32_e32 v142, 2, v120
	v_cndmask_b32_e32 v3, v3, v116, vcc
	v_rsq_f32_e32 v3, v3
	s_nop 0
	v_mul_f32_e32 v116, 0x45800000, v3
	v_cndmask_b32_e32 v116, v3, v116, vcc
	v_pk_mul_f32 v[132:133], v[116:117], v[132:133] op_sel_hi:[0,1]
	v_pk_mul_f32 v[146:147], v[116:117], v[138:139] op_sel_hi:[0,1]
	s_waitcnt vmcnt(0)
	v_pk_mul_f32 v[138:139], v[134:135], v[136:137] op_sel_hi:[0,1]
	v_pk_mul_f32 v[150:151], v[138:139], v[132:133]
	v_pk_mul_f32 v[136:137], v[134:135], v[144:145] op_sel_hi:[0,1]
	v_pk_mul_f32 v[148:149], v[136:137], v[146:147]
	v_mov_b32_e32 v116, v150
	v_mov_b32_e32 v145, v151
	v_mov_b32_e32 v146, v149
	v_mov_b32_e32 v152, v148
	s_and_saveexec_b64 s[12:13], s[0:1]
	s_cbranch_execz .LBB0_312
	v_mov_b32_e32 v143, v1
	v_lshl_add_u64 v[132:133], s[6:7], 0, v[142:143]
	global_load_dword v116, v[132:133], off
	v_add_co_u32_e32 v132, vcc, 0x2000, v132
	v_mov_b32_e32 v141, v1
	s_nop 0
	v_addc_co_u32_e32 v133, vcc, 0, v133, vcc
	global_load_dword v120, v[132:133], off
	v_lshl_add_u64 v[132:133], s[6:7], 0, v[140:141]
	global_load_dword v135, v[132:133], off
	v_add_co_u32_e32 v132, vcc, 0x2000, v132
	s_waitcnt vmcnt(0) lgkmcnt(0)
	v_pk_mul_f32 v[154:155], v[150:151], v[120:121] op_sel:[1,0] op_sel_hi:[0,0]
	v_addc_co_u32_e32 v133, vcc, 0, v133, vcc
	global_load_dword v134, v[132:133], off
	v_pk_mul_f32 v[132:133], v[150:151], v[116:117] op_sel_hi:[1,0]
	v_pk_fma_f32 v[144:145], v[150:151], v[116:117], v[154:155] op_sel_hi:[1,0,1]
	v_mul_f32_e32 v116, v149, v135
	v_mov_b32_e32 v152, v135
	s_waitcnt vmcnt(0) lgkmcnt(0)
	v_pk_fma_f32 v[146:147], v[148:149], v[134:135], v[116:117] op_sel_hi:[1,1,0] neg_lo:[1,0,0] neg_hi:[1,0,0]
	v_mov_b32_e32 v153, v134
	v_mul_f32_e32 v116, v149, v134
	v_pk_fma_f32 v[152:153], v[148:149], v[152:153], v[116:117] op_sel_hi:[1,1,0]
	v_sub_f32_e32 v116, v132, v154

; __device__ __forceinline__ void inproj_tile(const Params& p, char* smem, int l, int mt, int nt) {
;     ...
;         for (int j = 0; j < 4; ++j) {
;           float ss = 0.f;
; #pragma unroll
;           for (int n = 0; n < 4; ++n) ss += acc[m][n][j] * acc[m][n][j];
;           ss += __shfl_xor(ss, 1); ss += __shfl_xor(ss, 2); ss += __shfl_xor(ss, 4); ss += __shfl_xor(ss, 8);
;           float rstd = rsqrtf(ss * (1.f / 64.f) + EPSF);
;           int row = rowbase + m * 16 + fq * 4 + j;
;           float v[4];
; #pragma unroll
;           for (int n = 0; n < 4; ++n) v[n] = acc[m][n][j] * rstd * w4[n];
;           bool lat = row < MLAT;
;           float rv[4] = {v[0], v[1], v[2], v[3]};
;           if (lat) {
;             int t = row & 8191, pr = t >> 6, pc = t & 63;
;             float c0 = rope[pr * 16 + fr], s0 = rope[2048 + pr * 16 + fr];
;             float c1 = rope[pc * 16 + fr], s1 = rope[2048 + pc * 16 + fr];
;             rv[0] = v[0] * c0 - v[1] * s0; rv[1] = v[1] * c0 + v[0] * s0;
;             rv[2] = v[2] * c1 - v[3] * s1; rv[3] = v[3] * c1 + v[2] * s1;
;           }
.LBB0_321:
	s_or_b64 exec, exec, s[0:1]
	v_mov_b32_e32 v124, v121
	v_pk_mul_f32 v[144:145], v[124:125], v[124:125]
	v_mov_b32_e32 v116, v129
	v_pk_mul_f32 v[128:129], v[116:117], v[116:117]
	v_add_f32_e32 v3, v144, v145
	v_add_f32_e32 v3, v129, v3
	v_add_f32_e32 v3, v128, v3
	s_nop 1
	v_mov_b32_dpp v120, v3 quad_perm:[1,0,3,2] row_mask:0xf bank_mask:0xf
	s_waitcnt lgkmcnt(0)
	v_add_f32_e32 v3, v3, v120
	s_nop 1
	v_mov_b32_dpp v120, v3 quad_perm:[2,3,0,1] row_mask:0xf bank_mask:0xf
	s_waitcnt lgkmcnt(0)
	v_add_f32_e32 v3, v3, v120
	s_nop 1
	v_mov_b32_dpp v120, v3 row_half_mirror row_mask:0xf bank_mask:0xf
	s_waitcnt lgkmcnt(0)
	v_add_f32_e32 v3, v3, v120
	s_nop 1
	v_mov_b32_dpp v120, v3 row_mirror row_mask:0xf bank_mask:0xf
	s_waitcnt lgkmcnt(0)
	v_add_f32_e32 v3, v3, v120
	v_fmamk_f32 v3, v3, 0x3c800000, v197
	v_cmp_gt_f32_e32 vcc, s92, v3
	v_mul_f32_e32 v120, 0x4b800000, v3
	s_nop 0
	v_cndmask_b32_e32 v3, v3, v120, vcc
	v_rsq_f32_e32 v3, v3
	s_nop 0
	v_mul_f32_e32 v120, 0x45800000, v3
	v_cndmask_b32_e32 v128, v3, v120, vcc
	v_mov_b32_e32 v120, v125
	v_pk_mul_f32 v[120:121], v[128:129], v[120:121] op_sel_hi:[0,1]
	v_pk_mul_f32 v[116:117], v[128:129], v[116:117] op_sel_hi:[0,1]
	v_pk_mul_f32 v[124:125], v[138:139], v[120:121]
	v_pk_mul_f32 v[116:117], v[136:137], v[116:117]
	v_or_b32_e32 v120, 1, v2
	v_cmp_gt_i32_e64 s[0:1], s91, v120
	v_mov_b32_e32 v3, v124
	v_mov_b32_e32 v129, v125
	v_mov_b32_e32 v144, v117
	v_mov_b32_e32 v146, v116
	s_and_saveexec_b64 s[10:11], s[0:1]
	s_cbranch_execz .LBB0_323
	v_lshlrev_b32_e32 v3, 4, v120
	s_movk_i32 s12, 0xd0
	v_and_or_b32 v3, v3, s12, v168
	v_mov_b32_e32 v143, v1
	v_lshlrev_b32_e32 v146, 2, v3
	v_mov_b32_e32 v147, v1
	v_lshl_add_u64 v[128:129], s[6:7], 0, v[142:143]
	v_lshl_add_u64 v[146:147], s[6:7], 0, v[146:147]
	global_load_dword v144, v[128:129], off
	global_load_dword v149, v[146:147], off
	v_add_co_u32_e32 v128, vcc, 0x2000, v128
	s_waitcnt vmcnt(0) lgkmcnt(0)
	v_pk_mul_f32 v[150:151], v[124:125], v[144:145] op_sel_hi:[1,0]
	v_addc_co_u32_e32 v129, vcc, 0, v129, vcc
	global_load_dword v128, v[128:129], off
	v_add_co_u32_e32 v146, vcc, 0x2000, v146
	s_nop 1
	v_addc_co_u32_e32 v147, vcc, 0, v147, vcc
	global_load_dword v148, v[146:147], off
	v_mov_b32_e32 v146, v149
	s_waitcnt vmcnt(0) lgkmcnt(0)
	v_pk_mul_f32 v[152:153], v[124:125], v[128:129] op_sel:[1,0] op_sel_hi:[0,0]
	v_pk_fma_f32 v[128:129], v[124:125], v[144:145], v[152:153] op_sel_hi:[1,0,1]
	v_sub_f32_e32 v3, v150, v152
	v_mul_f32_e32 v128, v117, v149
	v_pk_fma_f32 v[144:145], v[116:117], v[148:149], v[128:129] op_sel_hi:[1,1,0] neg_lo:[1,0,0] neg_hi:[1,0,0]
	v_mov_b32_e32 v147, v148
	v_mul_f32_e32 v128, v117, v148
	v_pk_fma_f32 v[146:147], v[116:117], v[146:147], v[128:129] op_sel_hi:[1,1,0]

; __device__ __forceinline__ void inproj_tile(const Params& p, char* smem, int l, int mt, int nt) {
;     ...
;         for (int j = 0; j < 4; ++j) {
;           float ss = 0.f;
; #pragma unroll
;           for (int n = 0; n < 4; ++n) ss += acc[m][n][j] * acc[m][n][j];
;           ss += __shfl_xor(ss, 1); ss += __shfl_xor(ss, 2); ss += __shfl_xor(ss, 4); ss += __shfl_xor(ss, 8);
;           float rstd = rsqrtf(ss * (1.f / 64.f) + EPSF);
;           int row = rowbase + m * 16 + fq * 4 + j;
;           float v[4];
; #pragma unroll
;           for (int n = 0; n < 4; ++n) v[n] = acc[m][n][j] * rstd * w4[n];
;           bool lat = row < MLAT;
;           float rv[4] = {v[0], v[1], v[2], v[3]};
;           if (lat) {
;             int t = row & 8191, pr = t >> 6, pc = t & 63;
;             float c0 = rope[pr * 16 + fr], s0 = rope[2048 + pr * 16 + fr];
;             float c1 = rope[pc * 16 + fr], s1 = rope[2048 + pc * 16 + fr];
;             rv[0] = v[0] * c0 - v[1] * s0; rv[1] = v[1] * c0 + v[0] * s0;
;             rv[2] = v[2] * c1 - v[3] * s1; rv[3] = v[3] * c1 + v[2] * s1;
;           }
.LBB0_331:
	s_or_b64 exec, exec, s[0:1]
	v_mov_b32_e32 v116, v122
	v_mov_b32_e32 v117, v126
	v_pk_mul_f32 v[116:117], v[116:117], v[116:117]
	v_mov_b32_e32 v120, v130
	v_mov_b32_e32 v121, v118
	v_pk_mul_f32 v[124:125], v[120:121], v[120:121]
	v_add_f32_e32 v3, v116, v117
	v_add_f32_e32 v3, v125, v3
	v_add_f32_e32 v3, v124, v3
	s_nop 1
	v_mov_b32_dpp v116, v3 quad_perm:[1,0,3,2] row_mask:0xf bank_mask:0xf
	v_mov_b32_e32 v124, v126
	v_mov_b32_e32 v125, v122
	s_waitcnt lgkmcnt(0)
	v_add_f32_e32 v3, v3, v116
	s_nop 1
	v_mov_b32_dpp v116, v3 quad_perm:[2,3,0,1] row_mask:0xf bank_mask:0xf
	s_waitcnt lgkmcnt(0)
	v_add_f32_e32 v3, v3, v116
	s_nop 1
	v_mov_b32_dpp v116, v3 row_half_mirror row_mask:0xf bank_mask:0xf
	s_waitcnt lgkmcnt(0)
	v_add_f32_e32 v3, v3, v116
	s_nop 1
	v_mov_b32_dpp v116, v3 row_mirror row_mask:0xf bank_mask:0xf
	s_waitcnt lgkmcnt(0)
	v_add_f32_e32 v3, v3, v116
	v_fmamk_f32 v3, v3, 0x3c800000, v197
	v_cmp_gt_f32_e32 vcc, s92, v3
	v_mul_f32_e32 v116, 0x4b800000, v3
	s_nop 0
	v_cndmask_b32_e32 v3, v3, v116, vcc
	v_rsq_f32_e32 v3, v3
	s_nop 0
	v_mul_f32_e32 v116, 0x45800000, v3
	v_cndmask_b32_e32 v116, v3, v116, vcc
	v_pk_mul_f32 v[124:125], v[116:117], v[124:125] op_sel_hi:[0,1]
	v_pk_mul_f32 v[116:117], v[116:117], v[120:121] op_sel_hi:[0,1]
	v_pk_mul_f32 v[124:125], v[138:139], v[124:125]
	v_pk_mul_f32 v[116:117], v[136:137], v[116:117]
	v_or_b32_e32 v120, 2, v2
	v_cmp_gt_i32_e64 s[0:1], s91, v120
	v_mov_b32_e32 v3, v124
	v_mov_b32_e32 v129, v125
	v_mov_b32_e32 v144, v117
	v_mov_b32_e32 v146, v116
	s_and_saveexec_b64 s[10:11], s[0:1]
	s_cbranch_execz .LBB0_333
	v_mov_b32_e32 v143, v1
	v_lshl_add_u64 v[128:129], s[6:7], 0, v[142:143]
	global_load_dword v118, v[128:129], off
	v_add_co_u32_e32 v128, vcc, 0x2000, v128
	v_lshlrev_b32_e32 v3, 4, v120
	s_movk_i32 s12, 0xe0
	v_addc_co_u32_e32 v129, vcc, 0, v129, vcc
	v_and_or_b32 v3, v3, s12, v168
	global_load_dword v122, v[128:129], off
	v_lshlrev_b32_e32 v128, 2, v3
	v_mov_b32_e32 v129, v1
	v_lshl_add_u64 v[128:129], s[6:7], 0, v[128:129]
	global_load_dword v147, v[128:129], off
	v_add_co_u32_e32 v128, vcc, 0x2000, v128
	s_waitcnt vmcnt(0) lgkmcnt(0)
	v_pk_mul_f32 v[148:149], v[124:125], v[118:119] op_sel_hi:[1,0]
	v_addc_co_u32_e32 v129, vcc, 0, v129, vcc
	global_load_dword v146, v[128:129], off
	v_pk_mul_f32 v[150:151], v[124:125], v[122:123] op_sel:[1,0] op_sel_hi:[0,0]
	v_pk_fma_f32 v[128:129], v[124:125], v[118:119], v[150:151] op_sel_hi:[1,0,1]
	v_sub_f32_e32 v3, v148, v150
	v_mul_f32_e32 v118, v117, v147
	v_mov_b32_e32 v152, v147
	s_waitcnt vmcnt(0) lgkmcnt(0)
	v_pk_fma_f32 v[144:145], v[116:117], v[146:147], v[118:119] op_sel_hi:[1,1,0] neg_lo:[1,0,0] neg_hi:[1,0,0]
	v_mov_b32_e32 v153, v146
	v_mul_f32_e32 v118, v117, v146
	v_pk_fma_f32 v[146:147], v[116:117], v[152:153], v[118:119] op_sel_hi:[1,1,0]

; __device__ __forceinline__ void inproj_tile(const Params& p, char* smem, int l, int mt, int nt) {
;     ...
;         for (int j = 0; j < 4; ++j) {
;           float ss = 0.f;
; #pragma unroll
;           for (int n = 0; n < 4; ++n) ss += acc[m][n][j] * acc[m][n][j];
;           ss += __shfl_xor(ss, 1); ss += __shfl_xor(ss, 2); ss += __shfl_xor(ss, 4); ss += __shfl_xor(ss, 8);
;           float rstd = rsqrtf(ss * (1.f / 64.f) + EPSF);
;           int row = rowbase + m * 16 + fq * 4 + j;
;           float v[4];
; #pragma unroll
;           for (int n = 0; n < 4; ++n) v[n] = acc[m][n][j] * rstd * w4[n];
;           bool lat = row < MLAT;
;           float rv[4] = {v[0], v[1], v[2], v[3]};
;           if (lat) {
;             int t = row & 8191, pr = t >> 6, pc = t & 63;
;             float c0 = rope[pr * 16 + fr], s0 = rope[2048 + pr * 16 + fr];
;             float c1 = rope[pc * 16 + fr], s1 = rope[2048 + pc * 16 + fr];
;             rv[0] = v[0] * c0 - v[1] * s0; rv[1] = v[1] * c0 + v[0] * s0;
;             rv[2] = v[2] * c1 - v[3] * s1; rv[3] = v[3] * c1 + v[2] * s1;
;           }
.LBB0_341:
	s_or_b64 exec, exec, s[0:1]
	v_mov_b32_e32 v126, v123
	v_pk_mul_f32 v[116:117], v[126:127], v[126:127]
	v_mov_b32_e32 v118, v131
	v_pk_mul_f32 v[120:121], v[118:119], v[118:119]
	v_add_f32_e32 v3, v116, v117
	v_add_f32_e32 v3, v121, v3
	v_add_f32_e32 v3, v120, v3
	s_nop 1
	v_mov_b32_dpp v116, v3 quad_perm:[1,0,3,2] row_mask:0xf bank_mask:0xf
	v_mov_b32_e32 v122, v127
	s_waitcnt lgkmcnt(0)
	v_add_f32_e32 v3, v3, v116
	s_nop 1
	v_mov_b32_dpp v116, v3 quad_perm:[2,3,0,1] row_mask:0xf bank_mask:0xf
	s_waitcnt lgkmcnt(0)
	v_add_f32_e32 v3, v3, v116
	s_nop 1
	v_mov_b32_dpp v116, v3 row_half_mirror row_mask:0xf bank_mask:0xf
	s_waitcnt lgkmcnt(0)
	v_add_f32_e32 v3, v3, v116
	s_nop 1
	v_mov_b32_dpp v116, v3 row_mirror row_mask:0xf bank_mask:0xf
	s_waitcnt lgkmcnt(0)
	v_add_f32_e32 v3, v3, v116
	v_fmamk_f32 v3, v3, 0x3c800000, v197
	v_cmp_gt_f32_e32 vcc, s92, v3
	v_mul_f32_e32 v116, 0x4b800000, v3
	s_nop 0
	v_cndmask_b32_e32 v3, v3, v116, vcc
	v_rsq_f32_e32 v3, v3
	s_nop 0
	v_mul_f32_e32 v116, 0x45800000, v3
	v_cndmask_b32_e32 v116, v3, v116, vcc
	v_pk_mul_f32 v[120:121], v[116:117], v[122:123] op_sel_hi:[0,1]
	v_pk_mul_f32 v[116:117], v[116:117], v[118:119] op_sel_hi:[0,1]
	v_pk_mul_f32 v[120:121], v[138:139], v[120:121]
	v_pk_mul_f32 v[116:117], v[136:137], v[116:117]
	v_or_b32_e32 v118, 3, v2
	v_cmp_gt_i32_e64 s[0:1], s91, v118
	v_mov_b32_e32 v3, v120
	v_mov_b32_e32 v123, v121
	v_mov_b32_e32 v124, v117
	v_mov_b32_e32 v126, v116
	s_and_saveexec_b64 s[10:11], s[0:1]
	s_cbranch_execz .LBB0_343
	v_lshlrev_b32_e32 v3, 4, v118
	s_movk_i32 s12, 0xf0
	v_and_or_b32 v3, v3, s12, v168
	v_mov_b32_e32 v143, v1
	v_lshlrev_b32_e32 v126, 2, v3
	v_mov_b32_e32 v127, v1
	v_lshl_add_u64 v[122:123], s[6:7], 0, v[142:143]
	v_lshl_add_u64 v[126:127], s[6:7], 0, v[126:127]
	global_load_dword v124, v[122:123], off
	global_load_dword v129, v[126:127], off
	v_add_co_u32_e32 v122, vcc, 0x2000, v122
	s_waitcnt vmcnt(0) lgkmcnt(0)
	v_pk_mul_f32 v[130:131], v[120:121], v[124:125] op_sel_hi:[1,0]
	v_addc_co_u32_e32 v123, vcc, 0, v123, vcc
	global_load_dword v122, v[122:123], off
	v_add_co_u32_e32 v126, vcc, 0x2000, v126
	s_nop 1
	v_addc_co_u32_e32 v127, vcc, 0, v127, vcc
	global_load_dword v128, v[126:127], off
	v_mov_b32_e32 v126, v129
	s_waitcnt vmcnt(0) lgkmcnt(0)
	v_pk_mul_f32 v[144:145], v[120:121], v[122:123] op_sel:[1,0] op_sel_hi:[0,0]
	v_pk_fma_f32 v[122:123], v[120:121], v[124:125], v[144:145] op_sel_hi:[1,0,1]
	v_sub_f32_e32 v3, v130, v144
	v_mul_f32_e32 v122, v117, v129
	v_pk_fma_f32 v[124:125], v[116:117], v[128:129], v[122:123] op_sel_hi:[1,1,0] neg_lo:[1,0,0] neg_hi:[1,0,0]
	v_mov_b32_e32 v127, v128
	v_mul_f32_e32 v122, v117, v128
	v_pk_fma_f32 v[126:127], v[116:117], v[126:127], v[122:123] op_sel_hi:[1,1,0]

; __device__ __forceinline__ void inproj_tile(const Params& p, char* smem, int l, int mt, int nt) {
;     ...
;         for (int j = 0; j < 4; ++j) {
;           float ss = 0.f;
; #pragma unroll
;           for (int n = 0; n < 4; ++n) ss += acc[m][n][j] * acc[m][n][j];
;           ss += __shfl_xor(ss, 1); ss += __shfl_xor(ss, 2); ss += __shfl_xor(ss, 4); ss += __shfl_xor(ss, 8);
;           float rstd = rsqrtf(ss * (1.f / 64.f) + EPSF);
;           int row = rowbase + m * 16 + fq * 4 + j;
;           float v[4];
; #pragma unroll
;           for (int n = 0; n < 4; ++n) v[n] = acc[m][n][j] * rstd * w4[n];
;           bool lat = row < MLAT;
;           float rv[4] = {v[0], v[1], v[2], v[3]};
;           if (lat) {
;             int t = row & 8191, pr = t >> 6, pc = t & 63;
;             float c0 = rope[pr * 16 + fr], s0 = rope[2048 + pr * 16 + fr];
;             float c1 = rope[pc * 16 + fr], s1 = rope[2048 + pc * 16 + fr];
;             rv[0] = v[0] * c0 - v[1] * s0; rv[1] = v[1] * c0 + v[0] * s0;
;             rv[2] = v[2] * c1 - v[3] * s1; rv[3] = v[3] * c1 + v[2] * s1;
;           }
.LBB0_351:
	s_or_b64 exec, exec, s[0:1]
	v_mov_b32_e32 v118, v104
	v_mov_b32_e32 v119, v108
	v_pk_mul_f32 v[118:119], v[118:119], v[118:119]
	v_mov_b32_e32 v122, v112
	v_mov_b32_e32 v123, v100
	v_pk_mul_f32 v[120:121], v[122:123], v[122:123]
	v_add_f32_e32 v3, v118, v119
	v_add_f32_e32 v3, v121, v3
	v_add_f32_e32 v3, v120, v3
	s_nop 1
	v_mov_b32_dpp v100, v3 quad_perm:[1,0,3,2] row_mask:0xf bank_mask:0xf
	v_mov_b32_e32 v118, v108
	v_mov_b32_e32 v119, v104
	v_or_b32_e32 v116, 16, v2
	v_cmp_gt_i32_e64 s[0:1], s91, v116
	s_waitcnt lgkmcnt(0)
	v_add_f32_e32 v3, v3, v100
	s_nop 1
	v_mov_b32_dpp v100, v3 quad_perm:[2,3,0,1] row_mask:0xf bank_mask:0xf
	s_waitcnt lgkmcnt(0)
	v_add_f32_e32 v3, v3, v100
	s_nop 1
	v_mov_b32_dpp v100, v3 row_half_mirror row_mask:0xf bank_mask:0xf
	s_waitcnt lgkmcnt(0)
	v_add_f32_e32 v3, v3, v100
	s_nop 1
	v_mov_b32_dpp v100, v3 row_mirror row_mask:0xf bank_mask:0xf
	s_waitcnt lgkmcnt(0)
	v_add_f32_e32 v3, v3, v100
	v_fmamk_f32 v3, v3, 0x3c800000, v197
	v_cmp_gt_f32_e32 vcc, s92, v3
	v_mul_f32_e32 v100, 0x4b800000, v3
	s_nop 0
	v_cndmask_b32_e32 v3, v3, v100, vcc
	v_rsq_f32_e32 v3, v3
	s_nop 0
	v_mul_f32_e32 v100, 0x45800000, v3
	v_cndmask_b32_e32 v100, v3, v100, vcc
	v_pk_mul_f32 v[118:119], v[100:101], v[118:119] op_sel_hi:[0,1]
	v_pk_mul_f32 v[120:121], v[138:139], v[118:119]
	v_pk_mul_f32 v[118:119], v[100:101], v[122:123] op_sel_hi:[0,1]
	v_pk_mul_f32 v[118:119], v[136:137], v[118:119]
	v_mov_b32_e32 v3, v120
	v_mov_b32_e32 v123, v121
	v_mov_b32_e32 v124, v119
	v_mov_b32_e32 v126, v118
	s_and_saveexec_b64 s[10:11], s[0:1]
	s_cbranch_execz .LBB0_353
	v_mov_b32_e32 v143, v1
	v_lshl_add_u64 v[122:123], s[6:7], 0, v[142:143]
	global_load_dword v100, v[122:123], off
	v_add_co_u32_e32 v122, vcc, 0x2000, v122
	v_lshlrev_b32_e32 v3, 4, v116
	s_movk_i32 s12, 0x1c0
	v_addc_co_u32_e32 v123, vcc, 0, v123, vcc
	v_and_or_b32 v3, v3, s12, v168
	global_load_dword v104, v[122:123], off
	v_lshlrev_b32_e32 v122, 2, v3
	v_mov_b32_e32 v123, v1
	v_lshl_add_u64 v[122:123], s[6:7], 0, v[122:123]
	global_load_dword v127, v[122:123], off
	v_add_co_u32_e32 v122, vcc, 0x2000, v122
	s_waitcnt vmcnt(0) lgkmcnt(0)
	v_pk_mul_f32 v[128:129], v[120:121], v[100:101] op_sel_hi:[1,0]
	v_addc_co_u32_e32 v123, vcc, 0, v123, vcc
	global_load_dword v126, v[122:123], off
	v_pk_mul_f32 v[130:131], v[120:121], v[104:105] op_sel:[1,0] op_sel_hi:[0,0]
	v_pk_fma_f32 v[122:123], v[120:121], v[100:101], v[130:131] op_sel_hi:[1,0,1]
	v_sub_f32_e32 v3, v128, v130
	v_mul_f32_e32 v100, v119, v127
	v_mov_b32_e32 v144, v127
	s_waitcnt vmcnt(0) lgkmcnt(0)
	v_pk_fma_f32 v[124:125], v[118:119], v[126:127], v[100:101] op_sel_hi:[1,1,0] neg_lo:[1,0,0] neg_hi:[1,0,0]
	v_mov_b32_e32 v145, v126
	v_mul_f32_e32 v100, v119, v126
	v_pk_fma_f32 v[126:127], v[118:119], v[144:145], v[100:101] op_sel_hi:[1,1,0]

; __device__ __forceinline__ void inproj_tile(const Params& p, char* smem, int l, int mt, int nt) {
;     ...
;         for (int j = 0; j < 4; ++j) {
;           float ss = 0.f;
; #pragma unroll
;           for (int n = 0; n < 4; ++n) ss += acc[m][n][j] * acc[m][n][j];
;           ss += __shfl_xor(ss, 1); ss += __shfl_xor(ss, 2); ss += __shfl_xor(ss, 4); ss += __shfl_xor(ss, 8);
;           float rstd = rsqrtf(ss * (1.f / 64.f) + EPSF);
;           int row = rowbase + m * 16 + fq * 4 + j;
;           float v[4];
; #pragma unroll
;           for (int n = 0; n < 4; ++n) v[n] = acc[m][n][j] * rstd * w4[n];
;           bool lat = row < MLAT;
;           float rv[4] = {v[0], v[1], v[2], v[3]};
;           if (lat) {
;             int t = row & 8191, pr = t >> 6, pc = t & 63;
;             float c0 = rope[pr * 16 + fr], s0 = rope[2048 + pr * 16 + fr];
;             float c1 = rope[pc * 16 + fr], s1 = rope[2048 + pc * 16 + fr];
;             rv[0] = v[0] * c0 - v[1] * s0; rv[1] = v[1] * c0 + v[0] * s0;
;             rv[2] = v[2] * c1 - v[3] * s1; rv[3] = v[3] * c1 + v[2] * s1;
;           }
.LBB0_361:
	s_or_b64 exec, exec, s[0:1]
	v_mov_b32_e32 v108, v105
	v_pk_mul_f32 v[116:117], v[108:109], v[108:109]
	v_mov_b32_e32 v100, v113
	v_pk_mul_f32 v[112:113], v[100:101], v[100:101]
	v_add_f32_e32 v3, v116, v117
	v_add_f32_e32 v3, v113, v3
	v_add_f32_e32 v3, v112, v3
	s_nop 1
	v_mov_b32_dpp v104, v3 quad_perm:[1,0,3,2] row_mask:0xf bank_mask:0xf
	s_waitcnt lgkmcnt(0)
	v_add_f32_e32 v3, v3, v104
	s_nop 1
	v_mov_b32_dpp v104, v3 quad_perm:[2,3,0,1] row_mask:0xf bank_mask:0xf
	s_waitcnt lgkmcnt(0)
	v_add_f32_e32 v3, v3, v104
	s_nop 1
	v_mov_b32_dpp v104, v3 row_half_mirror row_mask:0xf bank_mask:0xf
	s_waitcnt lgkmcnt(0)
	v_add_f32_e32 v3, v3, v104
	s_nop 1
	v_mov_b32_dpp v104, v3 row_mirror row_mask:0xf bank_mask:0xf
	s_waitcnt lgkmcnt(0)
	v_add_f32_e32 v3, v3, v104
	v_fmamk_f32 v3, v3, 0x3c800000, v197
	v_cmp_gt_f32_e32 vcc, s92, v3
	v_mul_f32_e32 v104, 0x4b800000, v3
	s_nop 0
	v_cndmask_b32_e32 v3, v3, v104, vcc
	v_rsq_f32_e32 v3, v3
	s_nop 0
	v_mul_f32_e32 v104, 0x45800000, v3
	v_cndmask_b32_e32 v112, v3, v104, vcc
	v_mov_b32_e32 v104, v109
	v_pk_mul_f32 v[104:105], v[112:113], v[104:105] op_sel_hi:[0,1]
	v_pk_mul_f32 v[100:101], v[112:113], v[100:101] op_sel_hi:[0,1]
	v_pk_mul_f32 v[108:109], v[138:139], v[104:105]
	v_pk_mul_f32 v[100:101], v[136:137], v[100:101]
	v_or_b32_e32 v104, 17, v2
	v_cmp_gt_i32_e64 s[0:1], s91, v104
	v_mov_b32_e32 v3, v108
	v_mov_b32_e32 v113, v109
	v_mov_b32_e32 v116, v101
	v_mov_b32_e32 v118, v100
	s_and_saveexec_b64 s[10:11], s[0:1]
	s_cbranch_execz .LBB0_363
	v_lshlrev_b32_e32 v3, 4, v104
	s_movk_i32 s12, 0x1d0
	v_and_or_b32 v3, v3, s12, v168
	v_mov_b32_e32 v143, v1
	v_lshlrev_b32_e32 v118, 2, v3
	v_mov_b32_e32 v119, v1
	v_lshl_add_u64 v[112:113], s[6:7], 0, v[142:143]
	v_lshl_add_u64 v[118:119], s[6:7], 0, v[118:119]
	global_load_dword v116, v[112:113], off
	global_load_dword v121, v[118:119], off
	v_add_co_u32_e32 v112, vcc, 0x2000, v112
	s_waitcnt vmcnt(0) lgkmcnt(0)
	v_pk_mul_f32 v[122:123], v[108:109], v[116:117] op_sel_hi:[1,0]
	v_addc_co_u32_e32 v113, vcc, 0, v113, vcc
	global_load_dword v112, v[112:113], off
	v_add_co_u32_e32 v118, vcc, 0x2000, v118
	s_nop 1
	v_addc_co_u32_e32 v119, vcc, 0, v119, vcc
	global_load_dword v120, v[118:119], off
	v_mov_b32_e32 v118, v121
	s_waitcnt vmcnt(0) lgkmcnt(0)
	v_pk_mul_f32 v[124:125], v[108:109], v[112:113] op_sel:[1,0] op_sel_hi:[0,0]
	v_pk_fma_f32 v[112:113], v[108:109], v[116:117], v[124:125] op_sel_hi:[1,0,1]
	v_sub_f32_e32 v3, v122, v124
	v_mul_f32_e32 v112, v101, v121
	v_pk_fma_f32 v[116:117], v[100:101], v[120:121], v[112:113] op_sel_hi:[1,1,0] neg_lo:[1,0,0] neg_hi:[1,0,0]
	v_mov_b32_e32 v119, v120
	v_mul_f32_e32 v112, v101, v120
	v_pk_fma_f32 v[118:119], v[100:101], v[118:119], v[112:113] op_sel_hi:[1,1,0]

; __device__ __forceinline__ void inproj_tile(const Params& p, char* smem, int l, int mt, int nt) {
;     ...
;         for (int j = 0; j < 4; ++j) {
;           float ss = 0.f;
; #pragma unroll
;           for (int n = 0; n < 4; ++n) ss += acc[m][n][j] * acc[m][n][j];
;           ss += __shfl_xor(ss, 1); ss += __shfl_xor(ss, 2); ss += __shfl_xor(ss, 4); ss += __shfl_xor(ss, 8);
;           float rstd = rsqrtf(ss * (1.f / 64.f) + EPSF);
;           int row = rowbase + m * 16 + fq * 4 + j;
;           float v[4];
; #pragma unroll
;           for (int n = 0; n < 4; ++n) v[n] = acc[m][n][j] * rstd * w4[n];
;           bool lat = row < MLAT;
;           float rv[4] = {v[0], v[1], v[2], v[3]};
;           if (lat) {
;             int t = row & 8191, pr = t >> 6, pc = t & 63;
;             float c0 = rope[pr * 16 + fr], s0 = rope[2048 + pr * 16 + fr];
;             float c1 = rope[pc * 16 + fr], s1 = rope[2048 + pc * 16 + fr];
;             rv[0] = v[0] * c0 - v[1] * s0; rv[1] = v[1] * c0 + v[0] * s0;
;             rv[2] = v[2] * c1 - v[3] * s1; rv[3] = v[3] * c1 + v[2] * s1;
;           }
.LBB0_371:
	s_or_b64 exec, exec, s[0:1]
	v_mov_b32_e32 v100, v106
	v_mov_b32_e32 v101, v110
	v_pk_mul_f32 v[100:101], v[100:101], v[100:101]
	v_mov_b32_e32 v104, v114
	v_mov_b32_e32 v105, v102
	v_pk_mul_f32 v[108:109], v[104:105], v[104:105]
	v_add_f32_e32 v3, v100, v101
	v_add_f32_e32 v3, v109, v3
	v_add_f32_e32 v3, v108, v3
	s_nop 1
	v_mov_b32_dpp v100, v3 quad_perm:[1,0,3,2] row_mask:0xf bank_mask:0xf
	v_mov_b32_e32 v108, v110
	v_mov_b32_e32 v109, v106
	s_waitcnt lgkmcnt(0)
	v_add_f32_e32 v3, v3, v100
	s_nop 1
	v_mov_b32_dpp v100, v3 quad_perm:[2,3,0,1] row_mask:0xf bank_mask:0xf
	s_waitcnt lgkmcnt(0)
	v_add_f32_e32 v3, v3, v100
	s_nop 1
	v_mov_b32_dpp v100, v3 row_half_mirror row_mask:0xf bank_mask:0xf
	s_waitcnt lgkmcnt(0)
	v_add_f32_e32 v3, v3, v100
	s_nop 1
	v_mov_b32_dpp v100, v3 row_mirror row_mask:0xf bank_mask:0xf
	s_waitcnt lgkmcnt(0)
	v_add_f32_e32 v3, v3, v100
	v_fmamk_f32 v3, v3, 0x3c800000, v197
	v_cmp_gt_f32_e32 vcc, s92, v3
	v_mul_f32_e32 v100, 0x4b800000, v3
	s_nop 0
	v_cndmask_b32_e32 v3, v3, v100, vcc
	v_rsq_f32_e32 v3, v3
	s_nop 0
	v_mul_f32_e32 v100, 0x45800000, v3
	v_cndmask_b32_e32 v100, v3, v100, vcc
	v_pk_mul_f32 v[108:109], v[100:101], v[108:109] op_sel_hi:[0,1]
	v_pk_mul_f32 v[100:101], v[100:101], v[104:105] op_sel_hi:[0,1]
	v_pk_mul_f32 v[108:109], v[138:139], v[108:109]
	v_pk_mul_f32 v[100:101], v[136:137], v[100:101]
	v_or_b32_e32 v104, 18, v2
	v_cmp_gt_i32_e64 s[0:1], s91, v104
	v_mov_b32_e32 v3, v108
	v_mov_b32_e32 v113, v109
	v_mov_b32_e32 v116, v101
	v_mov_b32_e32 v118, v100
	s_and_saveexec_b64 s[10:11], s[0:1]
	s_cbranch_execz .LBB0_373
	v_mov_b32_e32 v143, v1
	v_lshl_add_u64 v[112:113], s[6:7], 0, v[142:143]
	global_load_dword v102, v[112:113], off
	v_add_co_u32_e32 v112, vcc, 0x2000, v112
	v_lshlrev_b32_e32 v3, 4, v104
	s_nop 0
	v_addc_co_u32_e32 v113, vcc, 0, v113, vcc
	v_and_or_b32 v3, v3, s40, v168
	global_load_dword v106, v[112:113], off
	v_lshlrev_b32_e32 v112, 2, v3
	v_mov_b32_e32 v113, v1
	v_lshl_add_u64 v[112:113], s[6:7], 0, v[112:113]
	global_load_dword v119, v[112:113], off
	v_add_co_u32_e32 v112, vcc, 0x2000, v112
	s_waitcnt vmcnt(0) lgkmcnt(0)
	v_pk_mul_f32 v[120:121], v[108:109], v[102:103] op_sel_hi:[1,0]
	v_addc_co_u32_e32 v113, vcc, 0, v113, vcc
	global_load_dword v118, v[112:113], off
	v_pk_mul_f32 v[122:123], v[108:109], v[106:107] op_sel:[1,0] op_sel_hi:[0,0]
	v_pk_fma_f32 v[112:113], v[108:109], v[102:103], v[122:123] op_sel_hi:[1,0,1]
	v_sub_f32_e32 v3, v120, v122
	v_mul_f32_e32 v102, v101, v119
	v_mov_b32_e32 v124, v119
	s_waitcnt vmcnt(0) lgkmcnt(0)
	v_pk_fma_f32 v[116:117], v[100:101], v[118:119], v[102:103] op_sel_hi:[1,1,0] neg_lo:[1,0,0] neg_hi:[1,0,0]
	v_mov_b32_e32 v125, v118
	v_mul_f32_e32 v102, v101, v118
	v_pk_fma_f32 v[118:119], v[100:101], v[124:125], v[102:103] op_sel_hi:[1,1,0]

; __device__ __forceinline__ void inproj_tile(const Params& p, char* smem, int l, int mt, int nt) {
;     ...
;         for (int j = 0; j < 4; ++j) {
;           float ss = 0.f;
; #pragma unroll
;           for (int n = 0; n < 4; ++n) ss += acc[m][n][j] * acc[m][n][j];
;           ss += __shfl_xor(ss, 1); ss += __shfl_xor(ss, 2); ss += __shfl_xor(ss, 4); ss += __shfl_xor(ss, 8);
;           float rstd = rsqrtf(ss * (1.f / 64.f) + EPSF);
;           int row = rowbase + m * 16 + fq * 4 + j;
;           float v[4];
; #pragma unroll
;           for (int n = 0; n < 4; ++n) v[n] = acc[m][n][j] * rstd * w4[n];
;           bool lat = row < MLAT;
;           float rv[4] = {v[0], v[1], v[2], v[3]};
;           if (lat) {
;             int t = row & 8191, pr = t >> 6, pc = t & 63;
;             float c0 = rope[pr * 16 + fr], s0 = rope[2048 + pr * 16 + fr];
;             float c1 = rope[pc * 16 + fr], s1 = rope[2048 + pc * 16 + fr];
;             rv[0] = v[0] * c0 - v[1] * s0; rv[1] = v[1] * c0 + v[0] * s0;
;             rv[2] = v[2] * c1 - v[3] * s1; rv[3] = v[3] * c1 + v[2] * s1;
;           }
.LBB0_381:
	s_or_b64 exec, exec, s[0:1]
	v_mov_b32_e32 v110, v107
	v_pk_mul_f32 v[100:101], v[110:111], v[110:111]
	v_mov_b32_e32 v102, v115
	v_pk_mul_f32 v[104:105], v[102:103], v[102:103]
	v_add_f32_e32 v3, v100, v101
	v_add_f32_e32 v3, v105, v3
	v_add_f32_e32 v3, v104, v3
	s_nop 1
	v_mov_b32_dpp v100, v3 quad_perm:[1,0,3,2] row_mask:0xf bank_mask:0xf
	v_mov_b32_e32 v106, v111
	s_waitcnt lgkmcnt(0)
	v_add_f32_e32 v3, v3, v100
	s_nop 1
	v_mov_b32_dpp v100, v3 quad_perm:[2,3,0,1] row_mask:0xf bank_mask:0xf
	s_waitcnt lgkmcnt(0)
	v_add_f32_e32 v3, v3, v100
	s_nop 1
	v_mov_b32_dpp v100, v3 row_half_mirror row_mask:0xf bank_mask:0xf
	s_waitcnt lgkmcnt(0)
	v_add_f32_e32 v3, v3, v100
	s_nop 1
	v_mov_b32_dpp v100, v3 row_mirror row_mask:0xf bank_mask:0xf
	s_waitcnt lgkmcnt(0)
	v_add_f32_e32 v3, v3, v100
	v_fmamk_f32 v3, v3, 0x3c800000, v197
	v_cmp_gt_f32_e32 vcc, s92, v3
	v_mul_f32_e32 v100, 0x4b800000, v3
	s_nop 0
	v_cndmask_b32_e32 v3, v3, v100, vcc
	v_rsq_f32_e32 v3, v3
	s_nop 0
	v_mul_f32_e32 v100, 0x45800000, v3
	v_cndmask_b32_e32 v100, v3, v100, vcc
	v_pk_mul_f32 v[104:105], v[100:101], v[106:107] op_sel_hi:[0,1]
	v_pk_mul_f32 v[100:101], v[100:101], v[102:103] op_sel_hi:[0,1]
	v_pk_mul_f32 v[104:105], v[138:139], v[104:105]
	v_pk_mul_f32 v[100:101], v[136:137], v[100:101]
	v_or_b32_e32 v102, 19, v2
	v_cmp_gt_i32_e64 s[0:1], s91, v102
	v_mov_b32_e32 v3, v104
	v_mov_b32_e32 v107, v105
	v_mov_b32_e32 v108, v101
	v_mov_b32_e32 v110, v100
	s_and_saveexec_b64 s[10:11], s[0:1]
	s_cbranch_execz .LBB0_383
	v_lshlrev_b32_e32 v3, 4, v102
	s_movk_i32 s12, 0x1f0
	v_and_or_b32 v3, v3, s12, v168
	v_mov_b32_e32 v143, v1
	v_lshlrev_b32_e32 v110, 2, v3
	v_mov_b32_e32 v111, v1
	v_lshl_add_u64 v[106:107], s[6:7], 0, v[142:143]
	v_lshl_add_u64 v[110:111], s[6:7], 0, v[110:111]
	global_load_dword v108, v[106:107], off
	global_load_dword v113, v[110:111], off
	v_add_co_u32_e32 v106, vcc, 0x2000, v106
	s_waitcnt vmcnt(0) lgkmcnt(0)
	v_pk_mul_f32 v[114:115], v[104:105], v[108:109] op_sel_hi:[1,0]
	v_addc_co_u32_e32 v107, vcc, 0, v107, vcc
	global_load_dword v106, v[106:107], off
	v_add_co_u32_e32 v110, vcc, 0x2000, v110
	s_nop 1
	v_addc_co_u32_e32 v111, vcc, 0, v111, vcc
	global_load_dword v112, v[110:111], off
	v_mov_b32_e32 v110, v113
	s_waitcnt vmcnt(0) lgkmcnt(0)
	v_pk_mul_f32 v[116:117], v[104:105], v[106:107] op_sel:[1,0] op_sel_hi:[0,0]
	v_pk_fma_f32 v[106:107], v[104:105], v[108:109], v[116:117] op_sel_hi:[1,0,1]
	v_sub_f32_e32 v3, v114, v116
	v_mul_f32_e32 v106, v101, v113
	v_pk_fma_f32 v[108:109], v[100:101], v[112:113], v[106:107] op_sel_hi:[1,1,0] neg_lo:[1,0,0] neg_hi:[1,0,0]
	v_mov_b32_e32 v111, v112
	v_mul_f32_e32 v106, v101, v112
	v_pk_fma_f32 v[110:111], v[100:101], v[110:111], v[106:107] op_sel_hi:[1,1,0]

; __device__ __forceinline__ void inproj_tile(const Params& p, char* smem, int l, int mt, int nt) {
;     ...
;         for (int j = 0; j < 4; ++j) {
;           float ss = 0.f;
; #pragma unroll
;           for (int n = 0; n < 4; ++n) ss += acc[m][n][j] * acc[m][n][j];
;           ss += __shfl_xor(ss, 1); ss += __shfl_xor(ss, 2); ss += __shfl_xor(ss, 4); ss += __shfl_xor(ss, 8);
;           float rstd = rsqrtf(ss * (1.f / 64.f) + EPSF);
;           int row = rowbase + m * 16 + fq * 4 + j;
;           float v[4];
; #pragma unroll
;           for (int n = 0; n < 4; ++n) v[n] = acc[m][n][j] * rstd * w4[n];
;           bool lat = row < MLAT;
;           float rv[4] = {v[0], v[1], v[2], v[3]};
;           if (lat) {
;             int t = row & 8191, pr = t >> 6, pc = t & 63;
;             float c0 = rope[pr * 16 + fr], s0 = rope[2048 + pr * 16 + fr];
;             float c1 = rope[pc * 16 + fr], s1 = rope[2048 + pc * 16 + fr];
;             rv[0] = v[0] * c0 - v[1] * s0; rv[1] = v[1] * c0 + v[0] * s0;
;             rv[2] = v[2] * c1 - v[3] * s1; rv[3] = v[3] * c1 + v[2] * s1;
;           }
.LBB0_391:
	s_or_b64 exec, exec, s[0:1]
	v_mov_b32_e32 v102, v88
	v_mov_b32_e32 v103, v92
	v_pk_mul_f32 v[102:103], v[102:103], v[102:103]
	v_mov_b32_e32 v106, v96
	v_mov_b32_e32 v107, v84
	v_pk_mul_f32 v[104:105], v[106:107], v[106:107]
	v_add_f32_e32 v3, v102, v103
	v_add_f32_e32 v3, v105, v3
	v_add_f32_e32 v3, v104, v3
	s_nop 1
	v_mov_b32_dpp v84, v3 quad_perm:[1,0,3,2] row_mask:0xf bank_mask:0xf
	v_mov_b32_e32 v102, v92
	v_mov_b32_e32 v103, v88
	v_or_b32_e32 v100, 32, v2
	v_cmp_gt_i32_e64 s[0:1], s91, v100
	s_waitcnt lgkmcnt(0)
	v_add_f32_e32 v3, v3, v84
	s_nop 1
	v_mov_b32_dpp v84, v3 quad_perm:[2,3,0,1] row_mask:0xf bank_mask:0xf
	s_waitcnt lgkmcnt(0)
	v_add_f32_e32 v3, v3, v84
	s_nop 1
	v_mov_b32_dpp v84, v3 row_half_mirror row_mask:0xf bank_mask:0xf
	s_waitcnt lgkmcnt(0)
	v_add_f32_e32 v3, v3, v84
	s_nop 1
	v_mov_b32_dpp v84, v3 row_mirror row_mask:0xf bank_mask:0xf
	s_waitcnt lgkmcnt(0)
	v_add_f32_e32 v3, v3, v84
	v_fmamk_f32 v3, v3, 0x3c800000, v197
	v_cmp_gt_f32_e32 vcc, s92, v3
	v_mul_f32_e32 v84, 0x4b800000, v3
	s_nop 0
	v_cndmask_b32_e32 v3, v3, v84, vcc
	v_rsq_f32_e32 v3, v3
	s_nop 0
	v_mul_f32_e32 v84, 0x45800000, v3
	v_cndmask_b32_e32 v84, v3, v84, vcc
	v_pk_mul_f32 v[102:103], v[84:85], v[102:103] op_sel_hi:[0,1]
	v_pk_mul_f32 v[104:105], v[138:139], v[102:103]
	v_pk_mul_f32 v[102:103], v[84:85], v[106:107] op_sel_hi:[0,1]
	v_pk_mul_f32 v[102:103], v[136:137], v[102:103]
	v_mov_b32_e32 v3, v104
	v_mov_b32_e32 v107, v105
	v_mov_b32_e32 v108, v103
	v_mov_b32_e32 v110, v102
	s_and_saveexec_b64 s[10:11], s[0:1]
	s_cbranch_execz .LBB0_393
	v_mov_b32_e32 v143, v1
	v_lshl_add_u64 v[106:107], s[6:7], 0, v[142:143]
	global_load_dword v84, v[106:107], off
	v_add_co_u32_e32 v106, vcc, 0x2000, v106
	v_lshlrev_b32_e32 v3, 4, v100
	s_movk_i32 s12, 0x2c0
	v_addc_co_u32_e32 v107, vcc, 0, v107, vcc
	v_and_or_b32 v3, v3, s12, v168
	global_load_dword v88, v[106:107], off
	v_lshlrev_b32_e32 v106, 2, v3
	v_mov_b32_e32 v107, v1
	v_lshl_add_u64 v[106:107], s[6:7], 0, v[106:107]
	global_load_dword v111, v[106:107], off
	v_add_co_u32_e32 v106, vcc, 0x2000, v106
	s_waitcnt vmcnt(0) lgkmcnt(0)
	v_pk_mul_f32 v[112:113], v[104:105], v[84:85] op_sel_hi:[1,0]
	v_addc_co_u32_e32 v107, vcc, 0, v107, vcc
	global_load_dword v110, v[106:107], off
	v_pk_mul_f32 v[114:115], v[104:105], v[88:89] op_sel:[1,0] op_sel_hi:[0,0]
	v_pk_fma_f32 v[106:107], v[104:105], v[84:85], v[114:115] op_sel_hi:[1,0,1]
	v_sub_f32_e32 v3, v112, v114
	v_mul_f32_e32 v84, v103, v111
	v_mov_b32_e32 v116, v111
	s_waitcnt vmcnt(0) lgkmcnt(0)
	v_pk_fma_f32 v[108:109], v[102:103], v[110:111], v[84:85] op_sel_hi:[1,1,0] neg_lo:[1,0,0] neg_hi:[1,0,0]
	v_mov_b32_e32 v117, v110
	v_mul_f32_e32 v84, v103, v110
	v_pk_fma_f32 v[110:111], v[102:103], v[116:117], v[84:85] op_sel_hi:[1,1,0]

; __device__ __forceinline__ void inproj_tile(const Params& p, char* smem, int l, int mt, int nt) {
;     ...
;         for (int j = 0; j < 4; ++j) {
;           float ss = 0.f;
; #pragma unroll
;           for (int n = 0; n < 4; ++n) ss += acc[m][n][j] * acc[m][n][j];
;           ss += __shfl_xor(ss, 1); ss += __shfl_xor(ss, 2); ss += __shfl_xor(ss, 4); ss += __shfl_xor(ss, 8);
;           float rstd = rsqrtf(ss * (1.f / 64.f) + EPSF);
;           int row = rowbase + m * 16 + fq * 4 + j;
;           float v[4];
; #pragma unroll
;           for (int n = 0; n < 4; ++n) v[n] = acc[m][n][j] * rstd * w4[n];
;           bool lat = row < MLAT;
;           float rv[4] = {v[0], v[1], v[2], v[3]};
;           if (lat) {
;             int t = row & 8191, pr = t >> 6, pc = t & 63;
;             float c0 = rope[pr * 16 + fr], s0 = rope[2048 + pr * 16 + fr];
;             float c1 = rope[pc * 16 + fr], s1 = rope[2048 + pc * 16 + fr];
;             rv[0] = v[0] * c0 - v[1] * s0; rv[1] = v[1] * c0 + v[0] * s0;
;             rv[2] = v[2] * c1 - v[3] * s1; rv[3] = v[3] * c1 + v[2] * s1;
;           }
.LBB0_401:
	s_or_b64 exec, exec, s[0:1]
	v_mov_b32_e32 v92, v89
	v_pk_mul_f32 v[100:101], v[92:93], v[92:93]
	v_mov_b32_e32 v84, v97
	v_pk_mul_f32 v[96:97], v[84:85], v[84:85]
	v_add_f32_e32 v3, v100, v101
	v_add_f32_e32 v3, v97, v3
	v_add_f32_e32 v3, v96, v3
	s_nop 1
	v_mov_b32_dpp v88, v3 quad_perm:[1,0,3,2] row_mask:0xf bank_mask:0xf
	s_waitcnt lgkmcnt(0)
	v_add_f32_e32 v3, v3, v88
	s_nop 1
	v_mov_b32_dpp v88, v3 quad_perm:[2,3,0,1] row_mask:0xf bank_mask:0xf
	s_waitcnt lgkmcnt(0)
	v_add_f32_e32 v3, v3, v88
	s_nop 1
	v_mov_b32_dpp v88, v3 row_half_mirror row_mask:0xf bank_mask:0xf
	s_waitcnt lgkmcnt(0)
	v_add_f32_e32 v3, v3, v88
	s_nop 1
	v_mov_b32_dpp v88, v3 row_mirror row_mask:0xf bank_mask:0xf
	s_waitcnt lgkmcnt(0)
	v_add_f32_e32 v3, v3, v88
	v_fmamk_f32 v3, v3, 0x3c800000, v197
	v_cmp_gt_f32_e32 vcc, s92, v3
	v_mul_f32_e32 v88, 0x4b800000, v3
	s_nop 0
	v_cndmask_b32_e32 v3, v3, v88, vcc
	v_rsq_f32_e32 v3, v3
	s_nop 0
	v_mul_f32_e32 v88, 0x45800000, v3
	v_cndmask_b32_e32 v96, v3, v88, vcc
	v_mov_b32_e32 v88, v93
	v_pk_mul_f32 v[88:89], v[96:97], v[88:89] op_sel_hi:[0,1]
	v_pk_mul_f32 v[84:85], v[96:97], v[84:85] op_sel_hi:[0,1]
	v_pk_mul_f32 v[92:93], v[138:139], v[88:89]
	v_pk_mul_f32 v[84:85], v[136:137], v[84:85]
	v_or_b32_e32 v88, 33, v2
	v_cmp_gt_i32_e64 s[0:1], s91, v88
	v_mov_b32_e32 v3, v92
	v_mov_b32_e32 v97, v93
	v_mov_b32_e32 v100, v85
	v_mov_b32_e32 v102, v84
	s_and_saveexec_b64 s[10:11], s[0:1]
	s_cbranch_execz .LBB0_403
	v_lshlrev_b32_e32 v3, 4, v88
	s_movk_i32 s12, 0x2d0
	v_and_or_b32 v3, v3, s12, v168
	v_mov_b32_e32 v143, v1
	v_lshlrev_b32_e32 v102, 2, v3
	v_mov_b32_e32 v103, v1
	v_lshl_add_u64 v[96:97], s[6:7], 0, v[142:143]
	v_lshl_add_u64 v[102:103], s[6:7], 0, v[102:103]
	global_load_dword v100, v[96:97], off
	global_load_dword v105, v[102:103], off
	v_add_co_u32_e32 v96, vcc, 0x2000, v96
	s_waitcnt vmcnt(0) lgkmcnt(0)
	v_pk_mul_f32 v[106:107], v[92:93], v[100:101] op_sel_hi:[1,0]
	v_addc_co_u32_e32 v97, vcc, 0, v97, vcc
	global_load_dword v96, v[96:97], off
	v_add_co_u32_e32 v102, vcc, 0x2000, v102
	s_nop 1
	v_addc_co_u32_e32 v103, vcc, 0, v103, vcc
	global_load_dword v104, v[102:103], off
	v_mov_b32_e32 v102, v105
	s_waitcnt vmcnt(0) lgkmcnt(0)
	v_pk_mul_f32 v[108:109], v[92:93], v[96:97] op_sel:[1,0] op_sel_hi:[0,0]
	v_pk_fma_f32 v[96:97], v[92:93], v[100:101], v[108:109] op_sel_hi:[1,0,1]
	v_sub_f32_e32 v3, v106, v108
	v_mul_f32_e32 v96, v85, v105
	v_pk_fma_f32 v[100:101], v[84:85], v[104:105], v[96:97] op_sel_hi:[1,1,0] neg_lo:[1,0,0] neg_hi:[1,0,0]
	v_mov_b32_e32 v103, v104
	v_mul_f32_e32 v96, v85, v104
	v_pk_fma_f32 v[102:103], v[84:85], v[102:103], v[96:97] op_sel_hi:[1,1,0]

; __device__ __forceinline__ void inproj_tile(const Params& p, char* smem, int l, int mt, int nt) {
;     ...
;         for (int j = 0; j < 4; ++j) {
;           float ss = 0.f;
; #pragma unroll
;           for (int n = 0; n < 4; ++n) ss += acc[m][n][j] * acc[m][n][j];
;           ss += __shfl_xor(ss, 1); ss += __shfl_xor(ss, 2); ss += __shfl_xor(ss, 4); ss += __shfl_xor(ss, 8);
;           float rstd = rsqrtf(ss * (1.f / 64.f) + EPSF);
;           int row = rowbase + m * 16 + fq * 4 + j;
;           float v[4];
; #pragma unroll
;           for (int n = 0; n < 4; ++n) v[n] = acc[m][n][j] * rstd * w4[n];
;           bool lat = row < MLAT;
;           float rv[4] = {v[0], v[1], v[2], v[3]};
;           if (lat) {
;             int t = row & 8191, pr = t >> 6, pc = t & 63;
;             float c0 = rope[pr * 16 + fr], s0 = rope[2048 + pr * 16 + fr];
;             float c1 = rope[pc * 16 + fr], s1 = rope[2048 + pc * 16 + fr];
;             rv[0] = v[0] * c0 - v[1] * s0; rv[1] = v[1] * c0 + v[0] * s0;
;             rv[2] = v[2] * c1 - v[3] * s1; rv[3] = v[3] * c1 + v[2] * s1;
;           }
.LBB0_411:
	s_or_b64 exec, exec, s[0:1]
	v_mov_b32_e32 v84, v90
	v_mov_b32_e32 v85, v94
	v_pk_mul_f32 v[84:85], v[84:85], v[84:85]
	v_mov_b32_e32 v88, v98
	v_mov_b32_e32 v89, v86
	v_pk_mul_f32 v[92:93], v[88:89], v[88:89]
	v_add_f32_e32 v3, v84, v85
	v_add_f32_e32 v3, v93, v3
	v_add_f32_e32 v3, v92, v3
	s_nop 1
	v_mov_b32_dpp v84, v3 quad_perm:[1,0,3,2] row_mask:0xf bank_mask:0xf
	v_mov_b32_e32 v92, v94
	v_mov_b32_e32 v93, v90
	s_waitcnt lgkmcnt(0)
	v_add_f32_e32 v3, v3, v84
	s_nop 1
	v_mov_b32_dpp v84, v3 quad_perm:[2,3,0,1] row_mask:0xf bank_mask:0xf
	s_waitcnt lgkmcnt(0)
	v_add_f32_e32 v3, v3, v84
	s_nop 1
	v_mov_b32_dpp v84, v3 row_half_mirror row_mask:0xf bank_mask:0xf
	s_waitcnt lgkmcnt(0)
	v_add_f32_e32 v3, v3, v84
	s_nop 1
	v_mov_b32_dpp v84, v3 row_mirror row_mask:0xf bank_mask:0xf
	s_waitcnt lgkmcnt(0)
	v_add_f32_e32 v3, v3, v84
	v_fmamk_f32 v3, v3, 0x3c800000, v197
	v_cmp_gt_f32_e32 vcc, s92, v3
	v_mul_f32_e32 v84, 0x4b800000, v3
	s_nop 0
	v_cndmask_b32_e32 v3, v3, v84, vcc
	v_rsq_f32_e32 v3, v3
	s_nop 0
	v_mul_f32_e32 v84, 0x45800000, v3
	v_cndmask_b32_e32 v84, v3, v84, vcc
	v_pk_mul_f32 v[92:93], v[84:85], v[92:93] op_sel_hi:[0,1]
	v_pk_mul_f32 v[84:85], v[84:85], v[88:89] op_sel_hi:[0,1]
	v_pk_mul_f32 v[92:93], v[138:139], v[92:93]
	v_pk_mul_f32 v[84:85], v[136:137], v[84:85]
	v_or_b32_e32 v88, 34, v2
	v_cmp_gt_i32_e64 s[0:1], s91, v88
	v_mov_b32_e32 v3, v92
	v_mov_b32_e32 v97, v93
	v_mov_b32_e32 v100, v85
	v_mov_b32_e32 v102, v84
	s_and_saveexec_b64 s[10:11], s[0:1]
	s_cbranch_execz .LBB0_413
	v_mov_b32_e32 v143, v1
	v_lshl_add_u64 v[96:97], s[6:7], 0, v[142:143]
	global_load_dword v86, v[96:97], off
	v_add_co_u32_e32 v96, vcc, 0x2000, v96
	v_lshlrev_b32_e32 v3, 4, v88
	s_movk_i32 s12, 0x2e0
	v_addc_co_u32_e32 v97, vcc, 0, v97, vcc
	v_and_or_b32 v3, v3, s12, v168
	global_load_dword v90, v[96:97], off
	v_lshlrev_b32_e32 v96, 2, v3
	v_mov_b32_e32 v97, v1
	v_lshl_add_u64 v[96:97], s[6:7], 0, v[96:97]
	global_load_dword v103, v[96:97], off
	v_add_co_u32_e32 v96, vcc, 0x2000, v96
	s_waitcnt vmcnt(0) lgkmcnt(0)
	v_pk_mul_f32 v[104:105], v[92:93], v[86:87] op_sel_hi:[1,0]
	v_addc_co_u32_e32 v97, vcc, 0, v97, vcc
	global_load_dword v102, v[96:97], off
	v_pk_mul_f32 v[106:107], v[92:93], v[90:91] op_sel:[1,0] op_sel_hi:[0,0]
	v_pk_fma_f32 v[96:97], v[92:93], v[86:87], v[106:107] op_sel_hi:[1,0,1]
	v_sub_f32_e32 v3, v104, v106
	v_mul_f32_e32 v86, v85, v103
	v_mov_b32_e32 v108, v103
	s_waitcnt vmcnt(0) lgkmcnt(0)
	v_pk_fma_f32 v[100:101], v[84:85], v[102:103], v[86:87] op_sel_hi:[1,1,0] neg_lo:[1,0,0] neg_hi:[1,0,0]
	v_mov_b32_e32 v109, v102
	v_mul_f32_e32 v86, v85, v102
	v_pk_fma_f32 v[102:103], v[84:85], v[108:109], v[86:87] op_sel_hi:[1,1,0]

; __device__ __forceinline__ void inproj_tile(const Params& p, char* smem, int l, int mt, int nt) {
;     ...
;         for (int j = 0; j < 4; ++j) {
;           float ss = 0.f;
; #pragma unroll
;           for (int n = 0; n < 4; ++n) ss += acc[m][n][j] * acc[m][n][j];
;           ss += __shfl_xor(ss, 1); ss += __shfl_xor(ss, 2); ss += __shfl_xor(ss, 4); ss += __shfl_xor(ss, 8);
;           float rstd = rsqrtf(ss * (1.f / 64.f) + EPSF);
;           int row = rowbase + m * 16 + fq * 4 + j;
;           float v[4];
; #pragma unroll
;           for (int n = 0; n < 4; ++n) v[n] = acc[m][n][j] * rstd * w4[n];
;           bool lat = row < MLAT;
;           float rv[4] = {v[0], v[1], v[2], v[3]};
;           if (lat) {
;             int t = row & 8191, pr = t >> 6, pc = t & 63;
;             float c0 = rope[pr * 16 + fr], s0 = rope[2048 + pr * 16 + fr];
;             float c1 = rope[pc * 16 + fr], s1 = rope[2048 + pc * 16 + fr];
;             rv[0] = v[0] * c0 - v[1] * s0; rv[1] = v[1] * c0 + v[0] * s0;
;             rv[2] = v[2] * c1 - v[3] * s1; rv[3] = v[3] * c1 + v[2] * s1;
;           }
.LBB0_421:
	s_or_b64 exec, exec, s[0:1]
	v_mov_b32_e32 v94, v91
	v_pk_mul_f32 v[84:85], v[94:95], v[94:95]
	v_mov_b32_e32 v86, v99
	v_pk_mul_f32 v[88:89], v[86:87], v[86:87]
	v_add_f32_e32 v3, v84, v85
	v_add_f32_e32 v3, v89, v3
	v_add_f32_e32 v3, v88, v3
	s_nop 1
	v_mov_b32_dpp v84, v3 quad_perm:[1,0,3,2] row_mask:0xf bank_mask:0xf
	v_mov_b32_e32 v90, v95
	s_waitcnt lgkmcnt(0)
	v_add_f32_e32 v3, v3, v84
	s_nop 1
	v_mov_b32_dpp v84, v3 quad_perm:[2,3,0,1] row_mask:0xf bank_mask:0xf
	s_waitcnt lgkmcnt(0)
	v_add_f32_e32 v3, v3, v84
	s_nop 1
	v_mov_b32_dpp v84, v3 row_half_mirror row_mask:0xf bank_mask:0xf
	s_waitcnt lgkmcnt(0)
	v_add_f32_e32 v3, v3, v84
	s_nop 1
	v_mov_b32_dpp v84, v3 row_mirror row_mask:0xf bank_mask:0xf
	s_waitcnt lgkmcnt(0)
	v_add_f32_e32 v3, v3, v84
	v_fmamk_f32 v3, v3, 0x3c800000, v197
	v_cmp_gt_f32_e32 vcc, s92, v3
	v_mul_f32_e32 v84, 0x4b800000, v3
	s_nop 0
	v_cndmask_b32_e32 v3, v3, v84, vcc
	v_rsq_f32_e32 v3, v3
	s_nop 0
	v_mul_f32_e32 v84, 0x45800000, v3
	v_cndmask_b32_e32 v84, v3, v84, vcc
	v_pk_mul_f32 v[88:89], v[84:85], v[90:91] op_sel_hi:[0,1]
	v_pk_mul_f32 v[84:85], v[84:85], v[86:87] op_sel_hi:[0,1]
	v_pk_mul_f32 v[88:89], v[138:139], v[88:89]
	v_pk_mul_f32 v[84:85], v[136:137], v[84:85]
	v_or_b32_e32 v86, 35, v2
	v_cmp_gt_i32_e64 s[0:1], s91, v86
	v_mov_b32_e32 v3, v88
	v_mov_b32_e32 v91, v89
	v_mov_b32_e32 v92, v85
	v_mov_b32_e32 v94, v84
	s_and_saveexec_b64 s[10:11], s[0:1]
	s_cbranch_execz .LBB0_423
	v_lshlrev_b32_e32 v3, 4, v86
	s_movk_i32 s12, 0x2f0
	v_and_or_b32 v3, v3, s12, v168
	v_mov_b32_e32 v143, v1
	v_lshlrev_b32_e32 v94, 2, v3
	v_mov_b32_e32 v95, v1
	v_lshl_add_u64 v[90:91], s[6:7], 0, v[142:143]
	v_lshl_add_u64 v[94:95], s[6:7], 0, v[94:95]
	global_load_dword v92, v[90:91], off
	global_load_dword v97, v[94:95], off
	v_add_co_u32_e32 v90, vcc, 0x2000, v90
	s_waitcnt vmcnt(0) lgkmcnt(0)
	v_pk_mul_f32 v[98:99], v[88:89], v[92:93] op_sel_hi:[1,0]
	v_addc_co_u32_e32 v91, vcc, 0, v91, vcc
	global_load_dword v90, v[90:91], off
	v_add_co_u32_e32 v94, vcc, 0x2000, v94
	s_nop 1
	v_addc_co_u32_e32 v95, vcc, 0, v95, vcc
	global_load_dword v96, v[94:95], off
	v_mov_b32_e32 v94, v97
	s_waitcnt vmcnt(0) lgkmcnt(0)
	v_pk_mul_f32 v[100:101], v[88:89], v[90:91] op_sel:[1,0] op_sel_hi:[0,0]
	v_pk_fma_f32 v[90:91], v[88:89], v[92:93], v[100:101] op_sel_hi:[1,0,1]
	v_sub_f32_e32 v3, v98, v100
	v_mul_f32_e32 v90, v85, v97
	v_pk_fma_f32 v[92:93], v[84:85], v[96:97], v[90:91] op_sel_hi:[1,1,0] neg_lo:[1,0,0] neg_hi:[1,0,0]
	v_mov_b32_e32 v95, v96
	v_mul_f32_e32 v90, v85, v96
	v_pk_fma_f32 v[94:95], v[84:85], v[94:95], v[90:91] op_sel_hi:[1,1,0]

; __device__ __forceinline__ void inproj_tile(const Params& p, char* smem, int l, int mt, int nt) {
;     ...
;         for (int j = 0; j < 4; ++j) {
;           float ss = 0.f;
; #pragma unroll
;           for (int n = 0; n < 4; ++n) ss += acc[m][n][j] * acc[m][n][j];
;           ss += __shfl_xor(ss, 1); ss += __shfl_xor(ss, 2); ss += __shfl_xor(ss, 4); ss += __shfl_xor(ss, 8);
;           float rstd = rsqrtf(ss * (1.f / 64.f) + EPSF);
;           int row = rowbase + m * 16 + fq * 4 + j;
;           float v[4];
; #pragma unroll
;           for (int n = 0; n < 4; ++n) v[n] = acc[m][n][j] * rstd * w4[n];
;           bool lat = row < MLAT;
;           float rv[4] = {v[0], v[1], v[2], v[3]};
;           if (lat) {
;             int t = row & 8191, pr = t >> 6, pc = t & 63;
;             float c0 = rope[pr * 16 + fr], s0 = rope[2048 + pr * 16 + fr];
;             float c1 = rope[pc * 16 + fr], s1 = rope[2048 + pc * 16 + fr];
;             rv[0] = v[0] * c0 - v[1] * s0; rv[1] = v[1] * c0 + v[0] * s0;
;             rv[2] = v[2] * c1 - v[3] * s1; rv[3] = v[3] * c1 + v[2] * s1;
;           }
.LBB0_431:
	s_or_b64 exec, exec, s[0:1]
	v_mov_b32_e32 v86, v72
	v_mov_b32_e32 v87, v76
	v_pk_mul_f32 v[86:87], v[86:87], v[86:87]
	v_mov_b32_e32 v90, v80
	v_mov_b32_e32 v91, v68
	v_pk_mul_f32 v[88:89], v[90:91], v[90:91]
	v_add_f32_e32 v3, v86, v87
	v_add_f32_e32 v3, v89, v3
	v_add_f32_e32 v3, v88, v3
	s_nop 1
	v_mov_b32_dpp v68, v3 quad_perm:[1,0,3,2] row_mask:0xf bank_mask:0xf
	v_mov_b32_e32 v86, v76
	v_mov_b32_e32 v87, v72
	v_or_b32_e32 v84, 48, v2
	v_cmp_gt_i32_e64 s[0:1], s91, v84
	s_waitcnt lgkmcnt(0)
	v_add_f32_e32 v3, v3, v68
	s_nop 1
	v_mov_b32_dpp v68, v3 quad_perm:[2,3,0,1] row_mask:0xf bank_mask:0xf
	s_waitcnt lgkmcnt(0)
	v_add_f32_e32 v3, v3, v68
	s_nop 1
	v_mov_b32_dpp v68, v3 row_half_mirror row_mask:0xf bank_mask:0xf
	s_waitcnt lgkmcnt(0)
	v_add_f32_e32 v3, v3, v68
	s_nop 1
	v_mov_b32_dpp v68, v3 row_mirror row_mask:0xf bank_mask:0xf
	s_waitcnt lgkmcnt(0)
	v_add_f32_e32 v3, v3, v68
	v_fmamk_f32 v3, v3, 0x3c800000, v197
	v_cmp_gt_f32_e32 vcc, s92, v3
	v_mul_f32_e32 v68, 0x4b800000, v3
	s_nop 0
	v_cndmask_b32_e32 v3, v3, v68, vcc
	v_rsq_f32_e32 v3, v3
	s_nop 0
	v_mul_f32_e32 v68, 0x45800000, v3
	v_cndmask_b32_e32 v68, v3, v68, vcc
	v_pk_mul_f32 v[86:87], v[68:69], v[86:87] op_sel_hi:[0,1]
	v_pk_mul_f32 v[88:89], v[138:139], v[86:87]
	v_pk_mul_f32 v[86:87], v[68:69], v[90:91] op_sel_hi:[0,1]
	v_pk_mul_f32 v[86:87], v[136:137], v[86:87]
	v_mov_b32_e32 v3, v88
	v_mov_b32_e32 v91, v89
	v_mov_b32_e32 v92, v87
	v_mov_b32_e32 v94, v86
	s_and_saveexec_b64 s[10:11], s[0:1]
	s_cbranch_execz .LBB0_433
	v_mov_b32_e32 v143, v1
	v_lshl_add_u64 v[90:91], s[6:7], 0, v[142:143]
	global_load_dword v68, v[90:91], off
	v_add_co_u32_e32 v90, vcc, 0x2000, v90
	v_lshlrev_b32_e32 v3, 4, v84
	s_movk_i32 s12, 0x3c0
	v_addc_co_u32_e32 v91, vcc, 0, v91, vcc
	v_and_or_b32 v3, v3, s12, v168
	global_load_dword v72, v[90:91], off
	v_lshlrev_b32_e32 v90, 2, v3
	v_mov_b32_e32 v91, v1
	v_lshl_add_u64 v[90:91], s[6:7], 0, v[90:91]
	global_load_dword v95, v[90:91], off
	v_add_co_u32_e32 v90, vcc, 0x2000, v90
	s_waitcnt vmcnt(0) lgkmcnt(0)
	v_pk_mul_f32 v[96:97], v[88:89], v[68:69] op_sel_hi:[1,0]
	v_addc_co_u32_e32 v91, vcc, 0, v91, vcc
	global_load_dword v94, v[90:91], off
	v_pk_mul_f32 v[98:99], v[88:89], v[72:73] op_sel:[1,0] op_sel_hi:[0,0]
	v_pk_fma_f32 v[90:91], v[88:89], v[68:69], v[98:99] op_sel_hi:[1,0,1]
	v_sub_f32_e32 v3, v96, v98
	v_mul_f32_e32 v68, v87, v95
	v_mov_b32_e32 v100, v95
	s_waitcnt vmcnt(0) lgkmcnt(0)
	v_pk_fma_f32 v[92:93], v[86:87], v[94:95], v[68:69] op_sel_hi:[1,1,0] neg_lo:[1,0,0] neg_hi:[1,0,0]
	v_mov_b32_e32 v101, v94
	v_mul_f32_e32 v68, v87, v94
	v_pk_fma_f32 v[94:95], v[86:87], v[100:101], v[68:69] op_sel_hi:[1,1,0]

; __device__ __forceinline__ void inproj_tile(const Params& p, char* smem, int l, int mt, int nt) {
;     ...
;         for (int j = 0; j < 4; ++j) {
;           float ss = 0.f;
; #pragma unroll
;           for (int n = 0; n < 4; ++n) ss += acc[m][n][j] * acc[m][n][j];
;           ss += __shfl_xor(ss, 1); ss += __shfl_xor(ss, 2); ss += __shfl_xor(ss, 4); ss += __shfl_xor(ss, 8);
;           float rstd = rsqrtf(ss * (1.f / 64.f) + EPSF);
;           int row = rowbase + m * 16 + fq * 4 + j;
;           float v[4];
; #pragma unroll
;           for (int n = 0; n < 4; ++n) v[n] = acc[m][n][j] * rstd * w4[n];
;           bool lat = row < MLAT;
;           float rv[4] = {v[0], v[1], v[2], v[3]};
;           if (lat) {
;             int t = row & 8191, pr = t >> 6, pc = t & 63;
;             float c0 = rope[pr * 16 + fr], s0 = rope[2048 + pr * 16 + fr];
;             float c1 = rope[pc * 16 + fr], s1 = rope[2048 + pc * 16 + fr];
;             rv[0] = v[0] * c0 - v[1] * s0; rv[1] = v[1] * c0 + v[0] * s0;
;             rv[2] = v[2] * c1 - v[3] * s1; rv[3] = v[3] * c1 + v[2] * s1;
;           }
.LBB0_441:
	s_or_b64 exec, exec, s[0:1]
	v_mov_b32_e32 v76, v73
	v_pk_mul_f32 v[84:85], v[76:77], v[76:77]
	v_mov_b32_e32 v68, v81
	v_pk_mul_f32 v[80:81], v[68:69], v[68:69]
	v_add_f32_e32 v3, v84, v85
	v_add_f32_e32 v3, v81, v3
	v_add_f32_e32 v3, v80, v3
	s_nop 1
	v_mov_b32_dpp v72, v3 quad_perm:[1,0,3,2] row_mask:0xf bank_mask:0xf
	s_waitcnt lgkmcnt(0)
	v_add_f32_e32 v3, v3, v72
	s_nop 1
	v_mov_b32_dpp v72, v3 quad_perm:[2,3,0,1] row_mask:0xf bank_mask:0xf
	s_waitcnt lgkmcnt(0)
	v_add_f32_e32 v3, v3, v72
	s_nop 1
	v_mov_b32_dpp v72, v3 row_half_mirror row_mask:0xf bank_mask:0xf
	s_waitcnt lgkmcnt(0)
	v_add_f32_e32 v3, v3, v72
	s_nop 1
	v_mov_b32_dpp v72, v3 row_mirror row_mask:0xf bank_mask:0xf
	s_waitcnt lgkmcnt(0)
	v_add_f32_e32 v3, v3, v72
	v_fmamk_f32 v3, v3, 0x3c800000, v197
	v_cmp_gt_f32_e32 vcc, s92, v3
	v_mul_f32_e32 v72, 0x4b800000, v3
	s_nop 0
	v_cndmask_b32_e32 v3, v3, v72, vcc
	v_rsq_f32_e32 v3, v3
	s_nop 0
	v_mul_f32_e32 v72, 0x45800000, v3
	v_cndmask_b32_e32 v80, v3, v72, vcc
	v_mov_b32_e32 v72, v77
	v_pk_mul_f32 v[72:73], v[80:81], v[72:73] op_sel_hi:[0,1]
	v_pk_mul_f32 v[68:69], v[80:81], v[68:69] op_sel_hi:[0,1]
	v_pk_mul_f32 v[76:77], v[138:139], v[72:73]
	v_pk_mul_f32 v[68:69], v[136:137], v[68:69]
	v_or_b32_e32 v72, 49, v2
	v_cmp_gt_i32_e64 s[0:1], s91, v72
	v_mov_b32_e32 v3, v76
	v_mov_b32_e32 v81, v77
	v_mov_b32_e32 v84, v69
	v_mov_b32_e32 v86, v68
	s_and_saveexec_b64 s[10:11], s[0:1]
	s_cbranch_execz .LBB0_443
	v_lshlrev_b32_e32 v3, 4, v72
	s_movk_i32 s12, 0x3d0
	v_and_or_b32 v3, v3, s12, v168
	v_mov_b32_e32 v143, v1
	v_lshlrev_b32_e32 v86, 2, v3
	v_mov_b32_e32 v87, v1
	v_lshl_add_u64 v[80:81], s[6:7], 0, v[142:143]
	v_lshl_add_u64 v[86:87], s[6:7], 0, v[86:87]
	global_load_dword v84, v[80:81], off
	global_load_dword v89, v[86:87], off
	v_add_co_u32_e32 v80, vcc, 0x2000, v80
	s_waitcnt vmcnt(0) lgkmcnt(0)
	v_pk_mul_f32 v[90:91], v[76:77], v[84:85] op_sel_hi:[1,0]
	v_addc_co_u32_e32 v81, vcc, 0, v81, vcc
	global_load_dword v80, v[80:81], off
	v_add_co_u32_e32 v86, vcc, 0x2000, v86
	s_nop 1
	v_addc_co_u32_e32 v87, vcc, 0, v87, vcc
	global_load_dword v88, v[86:87], off
	v_mov_b32_e32 v86, v89
	s_waitcnt vmcnt(0) lgkmcnt(0)
	v_pk_mul_f32 v[92:93], v[76:77], v[80:81] op_sel:[1,0] op_sel_hi:[0,0]
	v_pk_fma_f32 v[80:81], v[76:77], v[84:85], v[92:93] op_sel_hi:[1,0,1]
	v_sub_f32_e32 v3, v90, v92
	v_mul_f32_e32 v80, v69, v89
	v_pk_fma_f32 v[84:85], v[68:69], v[88:89], v[80:81] op_sel_hi:[1,1,0] neg_lo:[1,0,0] neg_hi:[1,0,0]
	v_mov_b32_e32 v87, v88
	v_mul_f32_e32 v80, v69, v88
	v_pk_fma_f32 v[86:87], v[68:69], v[86:87], v[80:81] op_sel_hi:[1,1,0]

; __device__ __forceinline__ void inproj_tile(const Params& p, char* smem, int l, int mt, int nt) {
;     ...
;         for (int j = 0; j < 4; ++j) {
;           float ss = 0.f;
; #pragma unroll
;           for (int n = 0; n < 4; ++n) ss += acc[m][n][j] * acc[m][n][j];
;           ss += __shfl_xor(ss, 1); ss += __shfl_xor(ss, 2); ss += __shfl_xor(ss, 4); ss += __shfl_xor(ss, 8);
;           float rstd = rsqrtf(ss * (1.f / 64.f) + EPSF);
;           int row = rowbase + m * 16 + fq * 4 + j;
;           float v[4];
; #pragma unroll
;           for (int n = 0; n < 4; ++n) v[n] = acc[m][n][j] * rstd * w4[n];
;           bool lat = row < MLAT;
;           float rv[4] = {v[0], v[1], v[2], v[3]};
;           if (lat) {
;             int t = row & 8191, pr = t >> 6, pc = t & 63;
;             float c0 = rope[pr * 16 + fr], s0 = rope[2048 + pr * 16 + fr];
;             float c1 = rope[pc * 16 + fr], s1 = rope[2048 + pc * 16 + fr];
;             rv[0] = v[0] * c0 - v[1] * s0; rv[1] = v[1] * c0 + v[0] * s0;
;             rv[2] = v[2] * c1 - v[3] * s1; rv[3] = v[3] * c1 + v[2] * s1;
;           }
.LBB0_451:
	s_or_b64 exec, exec, s[0:1]
	v_mov_b32_e32 v68, v74
	v_mov_b32_e32 v69, v78
	v_pk_mul_f32 v[68:69], v[68:69], v[68:69]
	v_mov_b32_e32 v72, v82
	v_mov_b32_e32 v73, v70
	v_pk_mul_f32 v[76:77], v[72:73], v[72:73]
	v_add_f32_e32 v3, v68, v69
	v_add_f32_e32 v3, v77, v3
	v_add_f32_e32 v3, v76, v3
	s_nop 1
	v_mov_b32_dpp v68, v3 quad_perm:[1,0,3,2] row_mask:0xf bank_mask:0xf
	v_mov_b32_e32 v76, v78
	v_mov_b32_e32 v77, v74
	s_waitcnt lgkmcnt(0)
	v_add_f32_e32 v3, v3, v68
	s_nop 1
	v_mov_b32_dpp v68, v3 quad_perm:[2,3,0,1] row_mask:0xf bank_mask:0xf
	s_waitcnt lgkmcnt(0)
	v_add_f32_e32 v3, v3, v68
	s_nop 1
	v_mov_b32_dpp v68, v3 row_half_mirror row_mask:0xf bank_mask:0xf
	s_waitcnt lgkmcnt(0)
	v_add_f32_e32 v3, v3, v68
	s_nop 1
	v_mov_b32_dpp v68, v3 row_mirror row_mask:0xf bank_mask:0xf
	s_waitcnt lgkmcnt(0)
	v_add_f32_e32 v3, v3, v68
	v_fmamk_f32 v3, v3, 0x3c800000, v197
	v_cmp_gt_f32_e32 vcc, s92, v3
	v_mul_f32_e32 v68, 0x4b800000, v3
	s_nop 0
	v_cndmask_b32_e32 v3, v3, v68, vcc
	v_rsq_f32_e32 v3, v3
	s_nop 0
	v_mul_f32_e32 v68, 0x45800000, v3
	v_cndmask_b32_e32 v68, v3, v68, vcc
	v_pk_mul_f32 v[76:77], v[68:69], v[76:77] op_sel_hi:[0,1]
	v_pk_mul_f32 v[68:69], v[68:69], v[72:73] op_sel_hi:[0,1]
	v_pk_mul_f32 v[76:77], v[138:139], v[76:77]
	v_pk_mul_f32 v[68:69], v[136:137], v[68:69]
	v_or_b32_e32 v72, 50, v2
	v_cmp_gt_i32_e64 s[0:1], s91, v72
	v_mov_b32_e32 v3, v76
	v_mov_b32_e32 v81, v77
	v_mov_b32_e32 v84, v69
	v_mov_b32_e32 v86, v68
	s_and_saveexec_b64 s[10:11], s[0:1]
	s_cbranch_execz .LBB0_453
	v_mov_b32_e32 v143, v1
	v_lshl_add_u64 v[80:81], s[6:7], 0, v[142:143]
	global_load_dword v70, v[80:81], off
	v_add_co_u32_e32 v80, vcc, 0x2000, v80
	v_lshlrev_b32_e32 v3, 4, v72
	s_movk_i32 s12, 0x3e0
	v_addc_co_u32_e32 v81, vcc, 0, v81, vcc
	v_and_or_b32 v3, v3, s12, v168
	global_load_dword v74, v[80:81], off
	v_lshlrev_b32_e32 v80, 2, v3
	v_mov_b32_e32 v81, v1
	v_lshl_add_u64 v[80:81], s[6:7], 0, v[80:81]
	global_load_dword v87, v[80:81], off
	v_add_co_u32_e32 v80, vcc, 0x2000, v80
	s_waitcnt vmcnt(0) lgkmcnt(0)
	v_pk_mul_f32 v[88:89], v[76:77], v[70:71] op_sel_hi:[1,0]
	v_addc_co_u32_e32 v81, vcc, 0, v81, vcc
	global_load_dword v86, v[80:81], off
	v_pk_mul_f32 v[90:91], v[76:77], v[74:75] op_sel:[1,0] op_sel_hi:[0,0]
	v_pk_fma_f32 v[80:81], v[76:77], v[70:71], v[90:91] op_sel_hi:[1,0,1]
	v_sub_f32_e32 v3, v88, v90
	v_mul_f32_e32 v70, v69, v87
	v_mov_b32_e32 v92, v87
	s_waitcnt vmcnt(0) lgkmcnt(0)
	v_pk_fma_f32 v[84:85], v[68:69], v[86:87], v[70:71] op_sel_hi:[1,1,0] neg_lo:[1,0,0] neg_hi:[1,0,0]
	v_mov_b32_e32 v93, v86
	v_mul_f32_e32 v70, v69, v86
	v_pk_fma_f32 v[86:87], v[68:69], v[92:93], v[70:71] op_sel_hi:[1,1,0]

; __device__ __forceinline__ void inproj_tile(const Params& p, char* smem, int l, int mt, int nt) {
;     ...
;         for (int j = 0; j < 4; ++j) {
;           float ss = 0.f;
; #pragma unroll
;           for (int n = 0; n < 4; ++n) ss += acc[m][n][j] * acc[m][n][j];
;           ss += __shfl_xor(ss, 1); ss += __shfl_xor(ss, 2); ss += __shfl_xor(ss, 4); ss += __shfl_xor(ss, 8);
;           float rstd = rsqrtf(ss * (1.f / 64.f) + EPSF);
;           int row = rowbase + m * 16 + fq * 4 + j;
;           float v[4];
; #pragma unroll
;           for (int n = 0; n < 4; ++n) v[n] = acc[m][n][j] * rstd * w4[n];
;           bool lat = row < MLAT;
;           float rv[4] = {v[0], v[1], v[2], v[3]};
;           if (lat) {
;             int t = row & 8191, pr = t >> 6, pc = t & 63;
;             float c0 = rope[pr * 16 + fr], s0 = rope[2048 + pr * 16 + fr];
;             float c1 = rope[pc * 16 + fr], s1 = rope[2048 + pc * 16 + fr];
;             rv[0] = v[0] * c0 - v[1] * s0; rv[1] = v[1] * c0 + v[0] * s0;
;             rv[2] = v[2] * c1 - v[3] * s1; rv[3] = v[3] * c1 + v[2] * s1;
;           }
.LBB0_461:
	s_or_b64 exec, exec, s[0:1]
	v_mov_b32_e32 v78, v75
	v_pk_mul_f32 v[68:69], v[78:79], v[78:79]
	v_mov_b32_e32 v70, v83
	v_pk_mul_f32 v[72:73], v[70:71], v[70:71]
	v_add_f32_e32 v3, v68, v69
	v_add_f32_e32 v3, v73, v3
	v_add_f32_e32 v3, v72, v3
	s_nop 1
	v_mov_b32_dpp v68, v3 quad_perm:[1,0,3,2] row_mask:0xf bank_mask:0xf
	v_mov_b32_e32 v74, v79
	s_waitcnt lgkmcnt(0)
	v_add_f32_e32 v3, v3, v68
	s_nop 1
	v_mov_b32_dpp v68, v3 quad_perm:[2,3,0,1] row_mask:0xf bank_mask:0xf
	s_waitcnt lgkmcnt(0)
	v_add_f32_e32 v3, v3, v68
	s_nop 1
	v_mov_b32_dpp v68, v3 row_half_mirror row_mask:0xf bank_mask:0xf
	s_waitcnt lgkmcnt(0)
	v_add_f32_e32 v3, v3, v68
	s_nop 1
	v_mov_b32_dpp v68, v3 row_mirror row_mask:0xf bank_mask:0xf
	s_waitcnt lgkmcnt(0)
	v_add_f32_e32 v3, v3, v68
	v_fmamk_f32 v3, v3, 0x3c800000, v197
	v_cmp_gt_f32_e32 vcc, s92, v3
	v_mul_f32_e32 v68, 0x4b800000, v3
	s_nop 0
	v_cndmask_b32_e32 v3, v3, v68, vcc
	v_rsq_f32_e32 v3, v3
	s_nop 0
	v_mul_f32_e32 v68, 0x45800000, v3
	v_cndmask_b32_e32 v68, v3, v68, vcc
	v_pk_mul_f32 v[72:73], v[68:69], v[74:75] op_sel_hi:[0,1]
	v_pk_mul_f32 v[68:69], v[68:69], v[70:71] op_sel_hi:[0,1]
	v_pk_mul_f32 v[72:73], v[138:139], v[72:73]
	v_pk_mul_f32 v[68:69], v[136:137], v[68:69]
	v_or_b32_e32 v70, 51, v2
	v_cmp_gt_i32_e64 s[0:1], s91, v70
	v_mov_b32_e32 v3, v72
	v_mov_b32_e32 v75, v73
	v_mov_b32_e32 v76, v69
	v_mov_b32_e32 v78, v68
	s_and_saveexec_b64 s[10:11], s[0:1]
	s_cbranch_execz .LBB0_463
	v_lshlrev_b32_e32 v3, 4, v70
	s_movk_i32 s12, 0x3f0
	v_and_or_b32 v3, v3, s12, v168
	v_mov_b32_e32 v143, v1
	v_lshlrev_b32_e32 v78, 2, v3
	v_mov_b32_e32 v79, v1
	v_lshl_add_u64 v[74:75], s[6:7], 0, v[142:143]
	v_lshl_add_u64 v[78:79], s[6:7], 0, v[78:79]
	global_load_dword v76, v[74:75], off
	global_load_dword v81, v[78:79], off
	v_add_co_u32_e32 v74, vcc, 0x2000, v74
	s_waitcnt vmcnt(0) lgkmcnt(0)
	v_pk_mul_f32 v[82:83], v[72:73], v[76:77] op_sel_hi:[1,0]
	v_addc_co_u32_e32 v75, vcc, 0, v75, vcc
	global_load_dword v74, v[74:75], off
	v_add_co_u32_e32 v78, vcc, 0x2000, v78
	s_nop 1
	v_addc_co_u32_e32 v79, vcc, 0, v79, vcc
	global_load_dword v80, v[78:79], off
	v_mov_b32_e32 v78, v81
	s_waitcnt vmcnt(0) lgkmcnt(0)
	v_pk_mul_f32 v[84:85], v[72:73], v[74:75] op_sel:[1,0] op_sel_hi:[0,0]
	v_pk_fma_f32 v[74:75], v[72:73], v[76:77], v[84:85] op_sel_hi:[1,0,1]
	v_sub_f32_e32 v3, v82, v84
	v_mul_f32_e32 v74, v69, v81
	v_pk_fma_f32 v[76:77], v[68:69], v[80:81], v[74:75] op_sel_hi:[1,1,0] neg_lo:[1,0,0] neg_hi:[1,0,0]
	v_mov_b32_e32 v79, v80
	v_mul_f32_e32 v74, v69, v80
	v_pk_fma_f32 v[78:79], v[68:69], v[78:79], v[74:75] op_sel_hi:[1,1,0]

; __device__ __forceinline__ void inproj_tile(const Params& p, char* smem, int l, int mt, int nt) {
;     ...
;         for (int j = 0; j < 4; ++j) {
;           float ss = 0.f;
; #pragma unroll
;           for (int n = 0; n < 4; ++n) ss += acc[m][n][j] * acc[m][n][j];
;           ss += __shfl_xor(ss, 1); ss += __shfl_xor(ss, 2); ss += __shfl_xor(ss, 4); ss += __shfl_xor(ss, 8);
;           float rstd = rsqrtf(ss * (1.f / 64.f) + EPSF);
;           int row = rowbase + m * 16 + fq * 4 + j;
;           float v[4];
; #pragma unroll
;           for (int n = 0; n < 4; ++n) v[n] = acc[m][n][j] * rstd * w4[n];
;           bool lat = row < MLAT;
;           float rv[4] = {v[0], v[1], v[2], v[3]};
;           if (lat) {
;             int t = row & 8191, pr = t >> 6, pc = t & 63;
;             float c0 = rope[pr * 16 + fr], s0 = rope[2048 + pr * 16 + fr];
;             float c1 = rope[pc * 16 + fr], s1 = rope[2048 + pc * 16 + fr];
;             rv[0] = v[0] * c0 - v[1] * s0; rv[1] = v[1] * c0 + v[0] * s0;
;             rv[2] = v[2] * c1 - v[3] * s1; rv[3] = v[3] * c1 + v[2] * s1;
;           }
.LBB0_471:
	s_or_b64 exec, exec, s[0:1]
	v_mov_b32_e32 v68, v56
	v_mov_b32_e32 v69, v60
	v_pk_mul_f32 v[68:69], v[68:69], v[68:69]
	v_mov_b32_e32 v72, v64
	v_mov_b32_e32 v73, v52
	v_pk_mul_f32 v[74:75], v[72:73], v[72:73]
	v_add_f32_e32 v52, v68, v69
	v_add_f32_e32 v52, v75, v52
	v_add_f32_e32 v52, v74, v52
	s_nop 1
	v_mov_b32_dpp v64, v52 quad_perm:[1,0,3,2] row_mask:0xf bank_mask:0xf
	v_mov_b32_e32 v68, v60
	v_mov_b32_e32 v69, v56
	v_or_b32_e32 v70, 64, v2
	v_lshrrev_b32_e32 v3, 2, v70
	s_waitcnt lgkmcnt(0)
	v_add_f32_e32 v52, v52, v64
	s_nop 1
	v_mov_b32_dpp v64, v52 quad_perm:[2,3,0,1] row_mask:0xf bank_mask:0xf
	s_movk_i32 s0, 0x7f0
	v_and_or_b32 v3, v3, s0, v168
	v_cmp_gt_i32_e64 s[0:1], s91, v70
	s_waitcnt lgkmcnt(0)
	v_add_f32_e32 v52, v52, v64
	s_nop 1
	v_mov_b32_dpp v64, v52 row_half_mirror row_mask:0xf bank_mask:0xf
	s_waitcnt lgkmcnt(0)
	v_add_f32_e32 v52, v52, v64
	s_nop 1
	v_mov_b32_dpp v64, v52 row_mirror row_mask:0xf bank_mask:0xf
	s_waitcnt lgkmcnt(0)
	v_add_f32_e32 v52, v52, v64
	v_fmamk_f32 v52, v52, 0x3c800000, v197
	v_cmp_gt_f32_e32 vcc, s92, v52
	v_mul_f32_e32 v64, 0x4b800000, v52
	s_nop 0
	v_cndmask_b32_e32 v52, v52, v64, vcc
	v_rsq_f32_e32 v52, v52
	s_nop 0
	v_mul_f32_e32 v64, 0x45800000, v52
	v_cndmask_b32_e32 v52, v52, v64, vcc
	v_pk_mul_f32 v[68:69], v[52:53], v[68:69] op_sel_hi:[0,1]
	v_pk_mul_f32 v[74:75], v[138:139], v[68:69]
	v_pk_mul_f32 v[68:69], v[52:53], v[72:73] op_sel_hi:[0,1]
	v_pk_mul_f32 v[72:73], v[136:137], v[68:69]
	v_lshlrev_b32_e32 v68, 2, v3
	v_mov_b32_e32 v3, v74
	v_mov_b32_e32 v77, v75
	v_mov_b32_e32 v78, v73
	v_mov_b32_e32 v80, v72
	s_and_saveexec_b64 s[10:11], s[0:1]
	s_cbranch_execz .LBB0_473
	v_mov_b32_e32 v69, v1
	v_lshl_add_u64 v[76:77], s[6:7], 0, v[68:69]
	global_load_dword v52, v[76:77], off
	v_add_co_u32_e32 v76, vcc, 0x2000, v76
	v_mov_b32_e32 v141, v1
	s_nop 0
	v_addc_co_u32_e32 v77, vcc, 0, v77, vcc
	global_load_dword v56, v[76:77], off
	v_lshl_add_u64 v[76:77], s[6:7], 0, v[140:141]
	global_load_dword v81, v[76:77], off
	v_add_co_u32_e32 v76, vcc, 0x2000, v76
	s_waitcnt vmcnt(0) lgkmcnt(0)
	v_pk_mul_f32 v[82:83], v[74:75], v[52:53] op_sel_hi:[1,0]
	v_addc_co_u32_e32 v77, vcc, 0, v77, vcc
	global_load_dword v80, v[76:77], off
	v_pk_mul_f32 v[84:85], v[74:75], v[56:57] op_sel:[1,0] op_sel_hi:[0,0]
	v_pk_fma_f32 v[76:77], v[74:75], v[52:53], v[84:85] op_sel_hi:[1,0,1]
	v_mul_f32_e32 v52, v73, v81
	v_mov_b32_e32 v86, v81
	v_sub_f32_e32 v3, v82, v84
	s_waitcnt vmcnt(0) lgkmcnt(0)
	v_pk_fma_f32 v[78:79], v[72:73], v[80:81], v[52:53] op_sel_hi:[1,1,0] neg_lo:[1,0,0] neg_hi:[1,0,0]
	v_mov_b32_e32 v87, v80
	v_mul_f32_e32 v52, v73, v80
	v_pk_fma_f32 v[80:81], v[72:73], v[86:87], v[52:53] op_sel_hi:[1,1,0]

; __device__ __forceinline__ void inproj_tile(const Params& p, char* smem, int l, int mt, int nt) {
;     ...
;         for (int j = 0; j < 4; ++j) {
;           float ss = 0.f;
; #pragma unroll
;           for (int n = 0; n < 4; ++n) ss += acc[m][n][j] * acc[m][n][j];
;           ss += __shfl_xor(ss, 1); ss += __shfl_xor(ss, 2); ss += __shfl_xor(ss, 4); ss += __shfl_xor(ss, 8);
;           float rstd = rsqrtf(ss * (1.f / 64.f) + EPSF);
;           int row = rowbase + m * 16 + fq * 4 + j;
;           float v[4];
; #pragma unroll
;           for (int n = 0; n < 4; ++n) v[n] = acc[m][n][j] * rstd * w4[n];
;           bool lat = row < MLAT;
;           float rv[4] = {v[0], v[1], v[2], v[3]};
;           if (lat) {
;             int t = row & 8191, pr = t >> 6, pc = t & 63;
;             float c0 = rope[pr * 16 + fr], s0 = rope[2048 + pr * 16 + fr];
;             float c1 = rope[pc * 16 + fr], s1 = rope[2048 + pc * 16 + fr];
;             rv[0] = v[0] * c0 - v[1] * s0; rv[1] = v[1] * c0 + v[0] * s0;
;             rv[2] = v[2] * c1 - v[3] * s1; rv[3] = v[3] * c1 + v[2] * s1;
;           }
.LBB0_481:
	s_or_b64 exec, exec, s[0:1]
	v_mov_b32_e32 v60, v57
	v_pk_mul_f32 v[70:71], v[60:61], v[60:61]
	v_mov_b32_e32 v52, v65
	v_pk_mul_f32 v[64:65], v[52:53], v[52:53]
	v_add_f32_e32 v3, v70, v71
	v_add_f32_e32 v3, v65, v3
	v_add_f32_e32 v3, v64, v3
	s_nop 1
	v_mov_b32_dpp v56, v3 quad_perm:[1,0,3,2] row_mask:0xf bank_mask:0xf
	s_waitcnt lgkmcnt(0)
	v_add_f32_e32 v3, v3, v56
	s_nop 1
	v_mov_b32_dpp v56, v3 quad_perm:[2,3,0,1] row_mask:0xf bank_mask:0xf
	s_waitcnt lgkmcnt(0)
	v_add_f32_e32 v3, v3, v56
	s_nop 1
	v_mov_b32_dpp v56, v3 row_half_mirror row_mask:0xf bank_mask:0xf
	s_waitcnt lgkmcnt(0)
	v_add_f32_e32 v3, v3, v56
	s_nop 1
	v_mov_b32_dpp v56, v3 row_mirror row_mask:0xf bank_mask:0xf
	s_waitcnt lgkmcnt(0)
	v_add_f32_e32 v3, v3, v56
	v_fmamk_f32 v3, v3, 0x3c800000, v197
	v_cmp_gt_f32_e32 vcc, s92, v3
	v_mul_f32_e32 v56, 0x4b800000, v3
	s_nop 0
	v_cndmask_b32_e32 v3, v3, v56, vcc
	v_rsq_f32_e32 v3, v3
	s_nop 0
	v_mul_f32_e32 v56, 0x45800000, v3
	v_cndmask_b32_e32 v64, v3, v56, vcc
	v_mov_b32_e32 v56, v61
	v_pk_mul_f32 v[56:57], v[64:65], v[56:57] op_sel_hi:[0,1]
	v_pk_mul_f32 v[52:53], v[64:65], v[52:53] op_sel_hi:[0,1]
	v_pk_mul_f32 v[60:61], v[138:139], v[56:57]
	v_pk_mul_f32 v[52:53], v[136:137], v[52:53]
	v_or_b32_e32 v56, 0x41, v2
	v_cmp_gt_i32_e64 s[0:1], s91, v56
	v_mov_b32_e32 v3, v60
	v_mov_b32_e32 v65, v61
	v_mov_b32_e32 v70, v53
	v_mov_b32_e32 v72, v52
	s_and_saveexec_b64 s[10:11], s[0:1]
	s_cbranch_execz .LBB0_483
	v_lshlrev_b32_e32 v3, 4, v56
	s_movk_i32 s12, 0xd0
	v_and_or_b32 v3, v3, s12, v168
	v_mov_b32_e32 v69, v1
	v_lshlrev_b32_e32 v72, 2, v3
	v_mov_b32_e32 v73, v1
	v_lshl_add_u64 v[64:65], s[6:7], 0, v[68:69]
	v_lshl_add_u64 v[72:73], s[6:7], 0, v[72:73]
	global_load_dword v70, v[64:65], off
	global_load_dword v75, v[72:73], off
	v_add_co_u32_e32 v64, vcc, 0x2000, v64
	s_waitcnt vmcnt(0) lgkmcnt(0)
	v_pk_mul_f32 v[76:77], v[60:61], v[70:71] op_sel_hi:[1,0]
	v_addc_co_u32_e32 v65, vcc, 0, v65, vcc
	global_load_dword v64, v[64:65], off
	v_add_co_u32_e32 v72, vcc, 0x2000, v72
	s_nop 1
	v_addc_co_u32_e32 v73, vcc, 0, v73, vcc
	global_load_dword v74, v[72:73], off
	v_mov_b32_e32 v72, v75
	s_waitcnt vmcnt(0) lgkmcnt(0)
	v_pk_mul_f32 v[78:79], v[60:61], v[64:65] op_sel:[1,0] op_sel_hi:[0,0]
	v_pk_fma_f32 v[64:65], v[60:61], v[70:71], v[78:79] op_sel_hi:[1,0,1]
	v_sub_f32_e32 v3, v76, v78
	v_mul_f32_e32 v64, v53, v75
	v_pk_fma_f32 v[70:71], v[52:53], v[74:75], v[64:65] op_sel_hi:[1,1,0] neg_lo:[1,0,0] neg_hi:[1,0,0]
	v_mov_b32_e32 v73, v74
	v_mul_f32_e32 v64, v53, v74
	v_pk_fma_f32 v[72:73], v[52:53], v[72:73], v[64:65] op_sel_hi:[1,1,0]

; __device__ __forceinline__ void inproj_tile(const Params& p, char* smem, int l, int mt, int nt) {
;     ...
;         for (int j = 0; j < 4; ++j) {
;           float ss = 0.f;
; #pragma unroll
;           for (int n = 0; n < 4; ++n) ss += acc[m][n][j] * acc[m][n][j];
;           ss += __shfl_xor(ss, 1); ss += __shfl_xor(ss, 2); ss += __shfl_xor(ss, 4); ss += __shfl_xor(ss, 8);
;           float rstd = rsqrtf(ss * (1.f / 64.f) + EPSF);
;           int row = rowbase + m * 16 + fq * 4 + j;
;           float v[4];
; #pragma unroll
;           for (int n = 0; n < 4; ++n) v[n] = acc[m][n][j] * rstd * w4[n];
;           bool lat = row < MLAT;
;           float rv[4] = {v[0], v[1], v[2], v[3]};
;           if (lat) {
;             int t = row & 8191, pr = t >> 6, pc = t & 63;
;             float c0 = rope[pr * 16 + fr], s0 = rope[2048 + pr * 16 + fr];
;             float c1 = rope[pc * 16 + fr], s1 = rope[2048 + pc * 16 + fr];
;             rv[0] = v[0] * c0 - v[1] * s0; rv[1] = v[1] * c0 + v[0] * s0;
;             rv[2] = v[2] * c1 - v[3] * s1; rv[3] = v[3] * c1 + v[2] * s1;
;           }
.LBB0_491:
	s_or_b64 exec, exec, s[0:1]
	v_mov_b32_e32 v52, v58
	v_mov_b32_e32 v53, v62
	v_pk_mul_f32 v[52:53], v[52:53], v[52:53]
	v_mov_b32_e32 v56, v66
	v_mov_b32_e32 v57, v54
	v_pk_mul_f32 v[60:61], v[56:57], v[56:57]
	v_add_f32_e32 v3, v52, v53
	v_add_f32_e32 v3, v61, v3
	v_add_f32_e32 v3, v60, v3
	s_nop 1
	v_mov_b32_dpp v52, v3 quad_perm:[1,0,3,2] row_mask:0xf bank_mask:0xf
	v_mov_b32_e32 v60, v62
	v_mov_b32_e32 v61, v58
	s_waitcnt lgkmcnt(0)
	v_add_f32_e32 v3, v3, v52
	s_nop 1
	v_mov_b32_dpp v52, v3 quad_perm:[2,3,0,1] row_mask:0xf bank_mask:0xf
	s_waitcnt lgkmcnt(0)
	v_add_f32_e32 v3, v3, v52
	s_nop 1
	v_mov_b32_dpp v52, v3 row_half_mirror row_mask:0xf bank_mask:0xf
	s_waitcnt lgkmcnt(0)
	v_add_f32_e32 v3, v3, v52
	s_nop 1
	v_mov_b32_dpp v52, v3 row_mirror row_mask:0xf bank_mask:0xf
	s_waitcnt lgkmcnt(0)
	v_add_f32_e32 v3, v3, v52
	v_fmamk_f32 v3, v3, 0x3c800000, v197
	v_cmp_gt_f32_e32 vcc, s92, v3
	v_mul_f32_e32 v52, 0x4b800000, v3
	s_nop 0
	v_cndmask_b32_e32 v3, v3, v52, vcc
	v_rsq_f32_e32 v3, v3
	s_nop 0
	v_mul_f32_e32 v52, 0x45800000, v3
	v_cndmask_b32_e32 v52, v3, v52, vcc
	v_pk_mul_f32 v[60:61], v[52:53], v[60:61] op_sel_hi:[0,1]
	v_pk_mul_f32 v[52:53], v[52:53], v[56:57] op_sel_hi:[0,1]
	v_pk_mul_f32 v[60:61], v[138:139], v[60:61]
	v_pk_mul_f32 v[52:53], v[136:137], v[52:53]
	v_or_b32_e32 v56, 0x42, v2
	v_cmp_gt_i32_e64 s[0:1], s91, v56
	v_mov_b32_e32 v3, v60
	v_mov_b32_e32 v65, v61
	v_mov_b32_e32 v70, v53
	v_mov_b32_e32 v72, v52
	s_and_saveexec_b64 s[10:11], s[0:1]
	s_cbranch_execz .LBB0_493
	v_mov_b32_e32 v69, v1
	v_lshl_add_u64 v[64:65], s[6:7], 0, v[68:69]
	global_load_dword v54, v[64:65], off
	v_add_co_u32_e32 v64, vcc, 0x2000, v64
	v_lshlrev_b32_e32 v3, 4, v56
	s_movk_i32 s12, 0xe0
	v_addc_co_u32_e32 v65, vcc, 0, v65, vcc
	v_and_or_b32 v3, v3, s12, v168
	global_load_dword v58, v[64:65], off
	v_lshlrev_b32_e32 v64, 2, v3
	v_mov_b32_e32 v65, v1
	v_lshl_add_u64 v[64:65], s[6:7], 0, v[64:65]
	global_load_dword v73, v[64:65], off
	v_add_co_u32_e32 v64, vcc, 0x2000, v64
	s_waitcnt vmcnt(0) lgkmcnt(0)
	v_pk_mul_f32 v[74:75], v[60:61], v[54:55] op_sel_hi:[1,0]
	v_addc_co_u32_e32 v65, vcc, 0, v65, vcc
	global_load_dword v72, v[64:65], off
	v_pk_mul_f32 v[76:77], v[60:61], v[58:59] op_sel:[1,0] op_sel_hi:[0,0]
	v_pk_fma_f32 v[64:65], v[60:61], v[54:55], v[76:77] op_sel_hi:[1,0,1]
	v_sub_f32_e32 v3, v74, v76
	v_mul_f32_e32 v54, v53, v73
	v_mov_b32_e32 v78, v73
	s_waitcnt vmcnt(0) lgkmcnt(0)
	v_pk_fma_f32 v[70:71], v[52:53], v[72:73], v[54:55] op_sel_hi:[1,1,0] neg_lo:[1,0,0] neg_hi:[1,0,0]
	v_mov_b32_e32 v79, v72
	v_mul_f32_e32 v54, v53, v72
	v_pk_fma_f32 v[72:73], v[52:53], v[78:79], v[54:55] op_sel_hi:[1,1,0]

; __device__ __forceinline__ void inproj_tile(const Params& p, char* smem, int l, int mt, int nt) {
;     ...
;           float ss = 0.f;
; #pragma unroll
;           for (int n = 0; n < 4; ++n) ss += acc[m][n][j] * acc[m][n][j];
;           ss += __shfl_xor(ss, 1); ss += __shfl_xor(ss, 2); ss += __shfl_xor(ss, 4); ss += __shfl_xor(ss, 8);
;           float rstd = rsqrtf(ss * (1.f / 64.f) + EPSF);
;           int row = rowbase + m * 16 + fq * 4 + j;
;           float v[4];
; #pragma unroll
;           for (int n = 0; n < 4; ++n) v[n] = acc[m][n][j] * rstd * w4[n];
;           bool lat = row < MLAT;
;           float rv[4] = {v[0], v[1], v[2], v[3]};
;           if (lat) {
;             int t = row & 8191, pr = t >> 6, pc = t & 63;
;             float c0 = rope[pr * 16 + fr], s0 = rope[2048 + pr * 16 + fr];
;             float c1 = rope[pc * 16 + fr], s1 = rope[2048 + pc * 16 + fr];
;             rv[0] = v[0] * c0 - v[1] * s0; rv[1] = v[1] * c0 + v[0] * s0;
;             rv[2] = v[2] * c1 - v[3] * s1; rv[3] = v[3] * c1 + v[2] * s1;
.LBB0_501:
	s_or_b64 exec, exec, s[0:1]
	v_mov_b32_e32 v62, v59
	v_pk_mul_f32 v[52:53], v[62:63], v[62:63]
	v_mov_b32_e32 v54, v67
	v_pk_mul_f32 v[56:57], v[54:55], v[54:55]
	v_add_f32_e32 v3, v52, v53
	v_add_f32_e32 v3, v57, v3
	v_add_f32_e32 v3, v56, v3
	s_nop 1
	v_mov_b32_dpp v52, v3 quad_perm:[1,0,3,2] row_mask:0xf bank_mask:0xf
	v_mov_b32_e32 v58, v63
	s_waitcnt lgkmcnt(0)
	v_add_f32_e32 v3, v3, v52
	s_nop 1
	v_mov_b32_dpp v52, v3 quad_perm:[2,3,0,1] row_mask:0xf bank_mask:0xf
	s_waitcnt lgkmcnt(0)
	v_add_f32_e32 v3, v3, v52
	s_nop 1
	v_mov_b32_dpp v52, v3 row_half_mirror row_mask:0xf bank_mask:0xf
	s_waitcnt lgkmcnt(0)
	v_add_f32_e32 v3, v3, v52
	s_nop 1
	v_mov_b32_dpp v52, v3 row_mirror row_mask:0xf bank_mask:0xf
	s_waitcnt lgkmcnt(0)
	v_add_f32_e32 v3, v3, v52
	v_fmamk_f32 v3, v3, 0x3c800000, v197
	v_cmp_gt_f32_e32 vcc, s92, v3
	v_mul_f32_e32 v52, 0x4b800000, v3
	s_nop 0
	v_cndmask_b32_e32 v3, v3, v52, vcc
	v_rsq_f32_e32 v3, v3
	s_nop 0
	v_mul_f32_e32 v52, 0x45800000, v3
	v_cndmask_b32_e32 v52, v3, v52, vcc
	v_pk_mul_f32 v[56:57], v[52:53], v[58:59] op_sel_hi:[0,1]
	v_pk_mul_f32 v[52:53], v[52:53], v[54:55] op_sel_hi:[0,1]
	v_pk_mul_f32 v[56:57], v[138:139], v[56:57]
	v_pk_mul_f32 v[52:53], v[136:137], v[52:53]
	v_or_b32_e32 v54, 0x43, v2
	v_cmp_gt_i32_e64 s[0:1], s91, v54
	v_mov_b32_e32 v3, v56
	v_mov_b32_e32 v59, v57
	v_mov_b32_e32 v60, v53
	v_mov_b32_e32 v62, v52
	s_and_saveexec_b64 s[10:11], s[0:1]
	s_cbranch_execz .LBB0_503
	v_lshlrev_b32_e32 v3, 4, v54
	s_movk_i32 s12, 0xf0
	v_and_or_b32 v3, v3, s12, v168
	v_mov_b32_e32 v69, v1
	v_lshlrev_b32_e32 v62, 2, v3
	v_mov_b32_e32 v63, v1
	v_lshl_add_u64 v[58:59], s[6:7], 0, v[68:69]
	v_lshl_add_u64 v[62:63], s[6:7], 0, v[62:63]
	global_load_dword v60, v[58:59], off
	global_load_dword v65, v[62:63], off
	v_add_co_u32_e32 v58, vcc, 0x2000, v58
	s_waitcnt vmcnt(0) lgkmcnt(0)
	v_pk_mul_f32 v[66:67], v[56:57], v[60:61] op_sel_hi:[1,0]
	v_addc_co_u32_e32 v59, vcc, 0, v59, vcc
	global_load_dword v58, v[58:59], off
	v_add_co_u32_e32 v62, vcc, 0x2000, v62
	s_nop 1
	v_addc_co_u32_e32 v63, vcc, 0, v63, vcc
	global_load_dword v64, v[62:63], off
	v_mov_b32_e32 v62, v65
	s_waitcnt vmcnt(0) lgkmcnt(0)
	v_pk_mul_f32 v[68:69], v[56:57], v[58:59] op_sel:[1,0] op_sel_hi:[0,0]
	v_pk_fma_f32 v[58:59], v[56:57], v[60:61], v[68:69] op_sel_hi:[1,0,1]
	v_sub_f32_e32 v3, v66, v68
	v_mul_f32_e32 v58, v53, v65
	v_pk_fma_f32 v[60:61], v[52:53], v[64:65], v[58:59] op_sel_hi:[1,1,0] neg_lo:[1,0,0] neg_hi:[1,0,0]
	v_mov_b32_e32 v63, v64
	v_mul_f32_e32 v58, v53, v64
	v_pk_fma_f32 v[62:63], v[52:53], v[62:63], v[58:59] op_sel_hi:[1,1,0]

; __device__ __forceinline__ void inproj_tile(const Params& p, char* smem, int l, int mt, int nt) {
;     ...
;           float ss = 0.f;
; #pragma unroll
;           for (int n = 0; n < 4; ++n) ss += acc[m][n][j] * acc[m][n][j];
;           ss += __shfl_xor(ss, 1); ss += __shfl_xor(ss, 2); ss += __shfl_xor(ss, 4); ss += __shfl_xor(ss, 8);
;           float rstd = rsqrtf(ss * (1.f / 64.f) + EPSF);
;           int row = rowbase + m * 16 + fq * 4 + j;
;           float v[4];
; #pragma unroll
;           for (int n = 0; n < 4; ++n) v[n] = acc[m][n][j] * rstd * w4[n];
;           bool lat = row < MLAT;
;           float rv[4] = {v[0], v[1], v[2], v[3]};
;           if (lat) {
;             int t = row & 8191, pr = t >> 6, pc = t & 63;
;             float c0 = rope[pr * 16 + fr], s0 = rope[2048 + pr * 16 + fr];
;             float c1 = rope[pc * 16 + fr], s1 = rope[2048 + pc * 16 + fr];
;             rv[0] = v[0] * c0 - v[1] * s0; rv[1] = v[1] * c0 + v[0] * s0;
;             rv[2] = v[2] * c1 - v[3] * s1; rv[3] = v[3] * c1 + v[2] * s1;
.LBB0_511:
	s_or_b64 exec, exec, s[0:1]
	v_mov_b32_e32 v52, v40
	v_mov_b32_e32 v53, v44
	v_pk_mul_f32 v[52:53], v[52:53], v[52:53]
	v_mov_b32_e32 v56, v48
	v_mov_b32_e32 v57, v36
	v_pk_mul_f32 v[58:59], v[56:57], v[56:57]
	v_add_f32_e32 v36, v52, v53
	v_add_f32_e32 v36, v59, v36
	v_add_f32_e32 v36, v58, v36
	s_nop 1
	v_mov_b32_dpp v48, v36 quad_perm:[1,0,3,2] row_mask:0xf bank_mask:0xf
	v_mov_b32_e32 v52, v44
	v_mov_b32_e32 v53, v40
	v_or_b32_e32 v54, 0x50, v2
	v_lshrrev_b32_e32 v3, 2, v54
	s_waitcnt lgkmcnt(0)
	v_add_f32_e32 v36, v36, v48
	s_nop 1
	v_mov_b32_dpp v48, v36 quad_perm:[2,3,0,1] row_mask:0xf bank_mask:0xf
	s_movk_i32 s0, 0x7f0
	v_and_or_b32 v3, v3, s0, v168
	v_cmp_gt_i32_e64 s[0:1], s91, v54
	s_waitcnt lgkmcnt(0)
	v_add_f32_e32 v36, v36, v48
	s_nop 1
	v_mov_b32_dpp v48, v36 row_half_mirror row_mask:0xf bank_mask:0xf
	s_waitcnt lgkmcnt(0)
	v_add_f32_e32 v36, v36, v48
	s_nop 1
	v_mov_b32_dpp v48, v36 row_mirror row_mask:0xf bank_mask:0xf
	s_waitcnt lgkmcnt(0)
	v_add_f32_e32 v36, v36, v48
	v_fmamk_f32 v36, v36, 0x3c800000, v197
	v_cmp_gt_f32_e32 vcc, s92, v36
	v_mul_f32_e32 v48, 0x4b800000, v36
	s_nop 0
	v_cndmask_b32_e32 v36, v36, v48, vcc
	v_rsq_f32_e32 v36, v36
	s_nop 0
	v_mul_f32_e32 v48, 0x45800000, v36
	v_cndmask_b32_e32 v36, v36, v48, vcc
	v_pk_mul_f32 v[52:53], v[36:37], v[52:53] op_sel_hi:[0,1]
	v_pk_mul_f32 v[58:59], v[138:139], v[52:53]
	v_pk_mul_f32 v[52:53], v[36:37], v[56:57] op_sel_hi:[0,1]
	v_pk_mul_f32 v[56:57], v[136:137], v[52:53]
	v_lshlrev_b32_e32 v52, 2, v3
	v_mov_b32_e32 v3, v58
	v_mov_b32_e32 v61, v59
	v_mov_b32_e32 v62, v57
	v_mov_b32_e32 v64, v56
	s_and_saveexec_b64 s[10:11], s[0:1]
	s_cbranch_execz .LBB0_513
	v_mov_b32_e32 v53, v1
	v_lshl_add_u64 v[60:61], s[6:7], 0, v[52:53]
	global_load_dword v36, v[60:61], off
	v_add_co_u32_e32 v60, vcc, 0x2000, v60
	v_lshlrev_b32_e32 v3, 4, v54
	s_movk_i32 s12, 0x1c0
	v_addc_co_u32_e32 v61, vcc, 0, v61, vcc
	v_and_or_b32 v3, v3, s12, v168
	global_load_dword v40, v[60:61], off
	v_lshlrev_b32_e32 v60, 2, v3
	v_mov_b32_e32 v61, v1
	v_lshl_add_u64 v[60:61], s[6:7], 0, v[60:61]
	global_load_dword v65, v[60:61], off
	v_add_co_u32_e32 v60, vcc, 0x2000, v60
	s_waitcnt vmcnt(0) lgkmcnt(0)
	v_pk_mul_f32 v[66:67], v[58:59], v[36:37] op_sel_hi:[1,0]
	v_addc_co_u32_e32 v61, vcc, 0, v61, vcc
	global_load_dword v64, v[60:61], off
	v_pk_mul_f32 v[68:69], v[58:59], v[40:41] op_sel:[1,0] op_sel_hi:[0,0]
	v_pk_fma_f32 v[60:61], v[58:59], v[36:37], v[68:69] op_sel_hi:[1,0,1]
	v_sub_f32_e32 v3, v66, v68
	v_mul_f32_e32 v36, v57, v65
	v_mov_b32_e32 v70, v65
	s_waitcnt vmcnt(0) lgkmcnt(0)
	v_pk_fma_f32 v[62:63], v[56:57], v[64:65], v[36:37] op_sel_hi:[1,1,0] neg_lo:[1,0,0] neg_hi:[1,0,0]
	v_mov_b32_e32 v71, v64
	v_mul_f32_e32 v36, v57, v64
	v_pk_fma_f32 v[64:65], v[56:57], v[70:71], v[36:37] op_sel_hi:[1,1,0]

; __device__ __forceinline__ void inproj_tile(const Params& p, char* smem, int l, int mt, int nt) {
;     ...
;           float ss = 0.f;
; #pragma unroll
;           for (int n = 0; n < 4; ++n) ss += acc[m][n][j] * acc[m][n][j];
;           ss += __shfl_xor(ss, 1); ss += __shfl_xor(ss, 2); ss += __shfl_xor(ss, 4); ss += __shfl_xor(ss, 8);
;           float rstd = rsqrtf(ss * (1.f / 64.f) + EPSF);
;           int row = rowbase + m * 16 + fq * 4 + j;
;           float v[4];
; #pragma unroll
;           for (int n = 0; n < 4; ++n) v[n] = acc[m][n][j] * rstd * w4[n];
;           bool lat = row < MLAT;
;           float rv[4] = {v[0], v[1], v[2], v[3]};
;           if (lat) {
;             int t = row & 8191, pr = t >> 6, pc = t & 63;
;             float c0 = rope[pr * 16 + fr], s0 = rope[2048 + pr * 16 + fr];
;             float c1 = rope[pc * 16 + fr], s1 = rope[2048 + pc * 16 + fr];
;             rv[0] = v[0] * c0 - v[1] * s0; rv[1] = v[1] * c0 + v[0] * s0;
;             rv[2] = v[2] * c1 - v[3] * s1; rv[3] = v[3] * c1 + v[2] * s1;
.LBB0_521:
	s_or_b64 exec, exec, s[0:1]
	v_mov_b32_e32 v44, v41
	v_pk_mul_f32 v[54:55], v[44:45], v[44:45]
	v_mov_b32_e32 v36, v49
	v_pk_mul_f32 v[48:49], v[36:37], v[36:37]
	v_add_f32_e32 v3, v54, v55
	v_add_f32_e32 v3, v49, v3
	v_add_f32_e32 v3, v48, v3
	s_nop 1
	v_mov_b32_dpp v40, v3 quad_perm:[1,0,3,2] row_mask:0xf bank_mask:0xf
	s_waitcnt lgkmcnt(0)
	v_add_f32_e32 v3, v3, v40
	s_nop 1
	v_mov_b32_dpp v40, v3 quad_perm:[2,3,0,1] row_mask:0xf bank_mask:0xf
	s_waitcnt lgkmcnt(0)
	v_add_f32_e32 v3, v3, v40
	s_nop 1
	v_mov_b32_dpp v40, v3 row_half_mirror row_mask:0xf bank_mask:0xf
	s_waitcnt lgkmcnt(0)
	v_add_f32_e32 v3, v3, v40
	s_nop 1
	v_mov_b32_dpp v40, v3 row_mirror row_mask:0xf bank_mask:0xf
	s_waitcnt lgkmcnt(0)
	v_add_f32_e32 v3, v3, v40
	v_fmamk_f32 v3, v3, 0x3c800000, v197
	v_cmp_gt_f32_e32 vcc, s92, v3
	v_mul_f32_e32 v40, 0x4b800000, v3
	s_nop 0
	v_cndmask_b32_e32 v3, v3, v40, vcc
	v_rsq_f32_e32 v3, v3
	s_nop 0
	v_mul_f32_e32 v40, 0x45800000, v3
	v_cndmask_b32_e32 v48, v3, v40, vcc
	v_mov_b32_e32 v40, v45
	v_pk_mul_f32 v[40:41], v[48:49], v[40:41] op_sel_hi:[0,1]
	v_pk_mul_f32 v[36:37], v[48:49], v[36:37] op_sel_hi:[0,1]
	v_pk_mul_f32 v[44:45], v[138:139], v[40:41]
	v_pk_mul_f32 v[36:37], v[136:137], v[36:37]
	v_or_b32_e32 v40, 0x51, v2
	v_cmp_gt_i32_e64 s[0:1], s91, v40
	v_mov_b32_e32 v3, v44
	v_mov_b32_e32 v49, v45
	v_mov_b32_e32 v54, v37
	v_mov_b32_e32 v56, v36
	s_and_saveexec_b64 s[10:11], s[0:1]
	s_cbranch_execz .LBB0_523
	v_lshlrev_b32_e32 v3, 4, v40
	s_movk_i32 s12, 0x1d0
	v_and_or_b32 v3, v3, s12, v168
	v_mov_b32_e32 v53, v1
	v_lshlrev_b32_e32 v56, 2, v3
	v_mov_b32_e32 v57, v1
	v_lshl_add_u64 v[48:49], s[6:7], 0, v[52:53]
	v_lshl_add_u64 v[56:57], s[6:7], 0, v[56:57]
	global_load_dword v54, v[48:49], off
	global_load_dword v59, v[56:57], off
	v_add_co_u32_e32 v48, vcc, 0x2000, v48
	s_waitcnt vmcnt(0) lgkmcnt(0)
	v_pk_mul_f32 v[60:61], v[44:45], v[54:55] op_sel_hi:[1,0]
	v_addc_co_u32_e32 v49, vcc, 0, v49, vcc
	global_load_dword v48, v[48:49], off
	v_add_co_u32_e32 v56, vcc, 0x2000, v56
	s_nop 1
	v_addc_co_u32_e32 v57, vcc, 0, v57, vcc
	global_load_dword v58, v[56:57], off
	v_mov_b32_e32 v56, v59
	s_waitcnt vmcnt(0) lgkmcnt(0)
	v_pk_mul_f32 v[62:63], v[44:45], v[48:49] op_sel:[1,0] op_sel_hi:[0,0]
	v_pk_fma_f32 v[48:49], v[44:45], v[54:55], v[62:63] op_sel_hi:[1,0,1]
	v_sub_f32_e32 v3, v60, v62
	v_mul_f32_e32 v48, v37, v59
	v_pk_fma_f32 v[54:55], v[36:37], v[58:59], v[48:49] op_sel_hi:[1,1,0] neg_lo:[1,0,0] neg_hi:[1,0,0]
	v_mov_b32_e32 v57, v58
	v_mul_f32_e32 v48, v37, v58
	v_pk_fma_f32 v[56:57], v[36:37], v[56:57], v[48:49] op_sel_hi:[1,1,0]

; __device__ __forceinline__ void inproj_tile(const Params& p, char* smem, int l, int mt, int nt) {
;     ...
;           float ss = 0.f;
; #pragma unroll
;           for (int n = 0; n < 4; ++n) ss += acc[m][n][j] * acc[m][n][j];
;           ss += __shfl_xor(ss, 1); ss += __shfl_xor(ss, 2); ss += __shfl_xor(ss, 4); ss += __shfl_xor(ss, 8);
;           float rstd = rsqrtf(ss * (1.f / 64.f) + EPSF);
;           int row = rowbase + m * 16 + fq * 4 + j;
;           float v[4];
; #pragma unroll
;           for (int n = 0; n < 4; ++n) v[n] = acc[m][n][j] * rstd * w4[n];
;           bool lat = row < MLAT;
;           float rv[4] = {v[0], v[1], v[2], v[3]};
;           if (lat) {
;             int t = row & 8191, pr = t >> 6, pc = t & 63;
;             float c0 = rope[pr * 16 + fr], s0 = rope[2048 + pr * 16 + fr];
;             float c1 = rope[pc * 16 + fr], s1 = rope[2048 + pc * 16 + fr];
;             rv[0] = v[0] * c0 - v[1] * s0; rv[1] = v[1] * c0 + v[0] * s0;
;             rv[2] = v[2] * c1 - v[3] * s1; rv[3] = v[3] * c1 + v[2] * s1;
.LBB0_531:
	s_or_b64 exec, exec, s[0:1]
	v_mov_b32_e32 v36, v42
	v_mov_b32_e32 v37, v46
	v_pk_mul_f32 v[36:37], v[36:37], v[36:37]
	v_mov_b32_e32 v40, v50
	v_mov_b32_e32 v41, v38
	v_pk_mul_f32 v[44:45], v[40:41], v[40:41]
	v_add_f32_e32 v3, v36, v37
	v_add_f32_e32 v3, v45, v3
	v_add_f32_e32 v3, v44, v3
	s_nop 1
	v_mov_b32_dpp v36, v3 quad_perm:[1,0,3,2] row_mask:0xf bank_mask:0xf
	v_mov_b32_e32 v44, v46
	v_mov_b32_e32 v45, v42
	s_waitcnt lgkmcnt(0)
	v_add_f32_e32 v3, v3, v36
	s_nop 1
	v_mov_b32_dpp v36, v3 quad_perm:[2,3,0,1] row_mask:0xf bank_mask:0xf
	s_waitcnt lgkmcnt(0)
	v_add_f32_e32 v3, v3, v36
	s_nop 1
	v_mov_b32_dpp v36, v3 row_half_mirror row_mask:0xf bank_mask:0xf
	s_waitcnt lgkmcnt(0)
	v_add_f32_e32 v3, v3, v36
	s_nop 1
	v_mov_b32_dpp v36, v3 row_mirror row_mask:0xf bank_mask:0xf
	s_waitcnt lgkmcnt(0)
	v_add_f32_e32 v3, v3, v36
	v_fmamk_f32 v3, v3, 0x3c800000, v197
	v_cmp_gt_f32_e32 vcc, s92, v3
	v_mul_f32_e32 v36, 0x4b800000, v3
	s_nop 0
	v_cndmask_b32_e32 v3, v3, v36, vcc
	v_rsq_f32_e32 v3, v3
	s_nop 0
	v_mul_f32_e32 v36, 0x45800000, v3
	v_cndmask_b32_e32 v36, v3, v36, vcc
	v_pk_mul_f32 v[44:45], v[36:37], v[44:45] op_sel_hi:[0,1]
	v_pk_mul_f32 v[36:37], v[36:37], v[40:41] op_sel_hi:[0,1]
	v_pk_mul_f32 v[44:45], v[138:139], v[44:45]
	v_pk_mul_f32 v[36:37], v[136:137], v[36:37]
	v_or_b32_e32 v40, 0x52, v2
	v_cmp_gt_i32_e64 s[0:1], s91, v40
	v_mov_b32_e32 v3, v44
	v_mov_b32_e32 v49, v45
	v_mov_b32_e32 v54, v37
	v_mov_b32_e32 v56, v36
	s_and_saveexec_b64 s[10:11], s[0:1]
	s_cbranch_execz .LBB0_533
	v_mov_b32_e32 v53, v1
	v_lshl_add_u64 v[48:49], s[6:7], 0, v[52:53]
	global_load_dword v38, v[48:49], off
	v_add_co_u32_e32 v48, vcc, 0x2000, v48
	v_lshlrev_b32_e32 v3, 4, v40
	s_nop 0
	v_addc_co_u32_e32 v49, vcc, 0, v49, vcc
	v_and_or_b32 v3, v3, s40, v168
	global_load_dword v42, v[48:49], off
	v_lshlrev_b32_e32 v48, 2, v3
	v_mov_b32_e32 v49, v1
	v_lshl_add_u64 v[48:49], s[6:7], 0, v[48:49]
	global_load_dword v57, v[48:49], off
	v_add_co_u32_e32 v48, vcc, 0x2000, v48
	s_waitcnt vmcnt(0) lgkmcnt(0)
	v_pk_mul_f32 v[58:59], v[44:45], v[38:39] op_sel_hi:[1,0]
	v_addc_co_u32_e32 v49, vcc, 0, v49, vcc
	global_load_dword v56, v[48:49], off
	v_pk_mul_f32 v[60:61], v[44:45], v[42:43] op_sel:[1,0] op_sel_hi:[0,0]
	v_pk_fma_f32 v[48:49], v[44:45], v[38:39], v[60:61] op_sel_hi:[1,0,1]
	v_sub_f32_e32 v3, v58, v60
	v_mul_f32_e32 v38, v37, v57
	v_mov_b32_e32 v62, v57
	s_waitcnt vmcnt(0) lgkmcnt(0)
	v_pk_fma_f32 v[54:55], v[36:37], v[56:57], v[38:39] op_sel_hi:[1,1,0] neg_lo:[1,0,0] neg_hi:[1,0,0]
	v_mov_b32_e32 v63, v56
	v_mul_f32_e32 v38, v37, v56
	v_pk_fma_f32 v[56:57], v[36:37], v[62:63], v[38:39] op_sel_hi:[1,1,0]

; __device__ __forceinline__ void inproj_tile(const Params& p, char* smem, int l, int mt, int nt) {
;     ...
;           float ss = 0.f;
; #pragma unroll
;           for (int n = 0; n < 4; ++n) ss += acc[m][n][j] * acc[m][n][j];
;           ss += __shfl_xor(ss, 1); ss += __shfl_xor(ss, 2); ss += __shfl_xor(ss, 4); ss += __shfl_xor(ss, 8);
;           float rstd = rsqrtf(ss * (1.f / 64.f) + EPSF);
;           int row = rowbase + m * 16 + fq * 4 + j;
;           float v[4];
; #pragma unroll
;           for (int n = 0; n < 4; ++n) v[n] = acc[m][n][j] * rstd * w4[n];
;           bool lat = row < MLAT;
;           float rv[4] = {v[0], v[1], v[2], v[3]};
;           if (lat) {
;             int t = row & 8191, pr = t >> 6, pc = t & 63;
;             float c0 = rope[pr * 16 + fr], s0 = rope[2048 + pr * 16 + fr];
;             float c1 = rope[pc * 16 + fr], s1 = rope[2048 + pc * 16 + fr];
;             rv[0] = v[0] * c0 - v[1] * s0; rv[1] = v[1] * c0 + v[0] * s0;
;             rv[2] = v[2] * c1 - v[3] * s1; rv[3] = v[3] * c1 + v[2] * s1;
.LBB0_541:
	s_or_b64 exec, exec, s[0:1]
	v_mov_b32_e32 v46, v43
	v_pk_mul_f32 v[36:37], v[46:47], v[46:47]
	v_mov_b32_e32 v38, v51
	v_pk_mul_f32 v[40:41], v[38:39], v[38:39]
	v_add_f32_e32 v3, v36, v37
	v_add_f32_e32 v3, v41, v3
	v_add_f32_e32 v3, v40, v3
	s_nop 1
	v_mov_b32_dpp v36, v3 quad_perm:[1,0,3,2] row_mask:0xf bank_mask:0xf
	v_mov_b32_e32 v42, v47
	s_waitcnt lgkmcnt(0)
	v_add_f32_e32 v3, v3, v36
	s_nop 1
	v_mov_b32_dpp v36, v3 quad_perm:[2,3,0,1] row_mask:0xf bank_mask:0xf
	s_waitcnt lgkmcnt(0)
	v_add_f32_e32 v3, v3, v36
	s_nop 1
	v_mov_b32_dpp v36, v3 row_half_mirror row_mask:0xf bank_mask:0xf
	s_waitcnt lgkmcnt(0)
	v_add_f32_e32 v3, v3, v36
	s_nop 1
	v_mov_b32_dpp v36, v3 row_mirror row_mask:0xf bank_mask:0xf
	s_waitcnt lgkmcnt(0)
	v_add_f32_e32 v3, v3, v36
	v_fmamk_f32 v3, v3, 0x3c800000, v197
	v_cmp_gt_f32_e32 vcc, s92, v3
	v_mul_f32_e32 v36, 0x4b800000, v3
	s_nop 0
	v_cndmask_b32_e32 v3, v3, v36, vcc
	v_rsq_f32_e32 v3, v3
	s_nop 0
	v_mul_f32_e32 v36, 0x45800000, v3
	v_cndmask_b32_e32 v36, v3, v36, vcc
	v_pk_mul_f32 v[40:41], v[36:37], v[42:43] op_sel_hi:[0,1]
	v_pk_mul_f32 v[36:37], v[36:37], v[38:39] op_sel_hi:[0,1]
	v_pk_mul_f32 v[40:41], v[138:139], v[40:41]
	v_pk_mul_f32 v[36:37], v[136:137], v[36:37]
	v_or_b32_e32 v38, 0x53, v2
	v_cmp_gt_i32_e64 s[0:1], s91, v38
	v_mov_b32_e32 v3, v40
	v_mov_b32_e32 v43, v41
	v_mov_b32_e32 v44, v37
	v_mov_b32_e32 v46, v36
	s_and_saveexec_b64 s[10:11], s[0:1]
	s_cbranch_execz .LBB0_543
	v_lshlrev_b32_e32 v3, 4, v38
	s_movk_i32 s12, 0x1f0
	v_and_or_b32 v3, v3, s12, v168
	v_mov_b32_e32 v53, v1
	v_lshlrev_b32_e32 v46, 2, v3
	v_mov_b32_e32 v47, v1
	v_lshl_add_u64 v[42:43], s[6:7], 0, v[52:53]
	v_lshl_add_u64 v[46:47], s[6:7], 0, v[46:47]
	global_load_dword v44, v[42:43], off
	global_load_dword v49, v[46:47], off
	v_add_co_u32_e32 v42, vcc, 0x2000, v42
	s_waitcnt vmcnt(0) lgkmcnt(0)
	v_pk_mul_f32 v[50:51], v[40:41], v[44:45] op_sel_hi:[1,0]
	v_addc_co_u32_e32 v43, vcc, 0, v43, vcc
	global_load_dword v42, v[42:43], off
	v_add_co_u32_e32 v46, vcc, 0x2000, v46
	s_nop 1
	v_addc_co_u32_e32 v47, vcc, 0, v47, vcc
	global_load_dword v48, v[46:47], off
	v_mov_b32_e32 v46, v49
	s_waitcnt vmcnt(0) lgkmcnt(0)
	v_pk_mul_f32 v[52:53], v[40:41], v[42:43] op_sel:[1,0] op_sel_hi:[0,0]
	v_pk_fma_f32 v[42:43], v[40:41], v[44:45], v[52:53] op_sel_hi:[1,0,1]
	v_sub_f32_e32 v3, v50, v52
	v_mul_f32_e32 v42, v37, v49
	v_pk_fma_f32 v[44:45], v[36:37], v[48:49], v[42:43] op_sel_hi:[1,1,0] neg_lo:[1,0,0] neg_hi:[1,0,0]
	v_mov_b32_e32 v47, v48
	v_mul_f32_e32 v42, v37, v48
	v_pk_fma_f32 v[46:47], v[36:37], v[46:47], v[42:43] op_sel_hi:[1,1,0]

; __device__ __forceinline__ void inproj_tile(const Params& p, char* smem, int l, int mt, int nt) {
;     ...
;           float ss = 0.f;
; #pragma unroll
;           for (int n = 0; n < 4; ++n) ss += acc[m][n][j] * acc[m][n][j];
;           ss += __shfl_xor(ss, 1); ss += __shfl_xor(ss, 2); ss += __shfl_xor(ss, 4); ss += __shfl_xor(ss, 8);
;           float rstd = rsqrtf(ss * (1.f / 64.f) + EPSF);
;           int row = rowbase + m * 16 + fq * 4 + j;
;           float v[4];
; #pragma unroll
;           for (int n = 0; n < 4; ++n) v[n] = acc[m][n][j] * rstd * w4[n];
;           bool lat = row < MLAT;
;           float rv[4] = {v[0], v[1], v[2], v[3]};
;           if (lat) {
;             int t = row & 8191, pr = t >> 6, pc = t & 63;
;             float c0 = rope[pr * 16 + fr], s0 = rope[2048 + pr * 16 + fr];
;             float c1 = rope[pc * 16 + fr], s1 = rope[2048 + pc * 16 + fr];
;             rv[0] = v[0] * c0 - v[1] * s0; rv[1] = v[1] * c0 + v[0] * s0;
;             rv[2] = v[2] * c1 - v[3] * s1; rv[3] = v[3] * c1 + v[2] * s1;
.LBB0_551:
	s_or_b64 exec, exec, s[0:1]
	v_mov_b32_e32 v36, v24
	v_mov_b32_e32 v37, v28
	v_pk_mul_f32 v[36:37], v[36:37], v[36:37]
	v_mov_b32_e32 v40, v32
	v_mov_b32_e32 v41, v20
	v_pk_mul_f32 v[42:43], v[40:41], v[40:41]
	v_add_f32_e32 v20, v36, v37
	v_add_f32_e32 v20, v43, v20
	v_add_f32_e32 v20, v42, v20
	s_nop 1
	v_mov_b32_dpp v32, v20 quad_perm:[1,0,3,2] row_mask:0xf bank_mask:0xf
	v_mov_b32_e32 v36, v28
	v_mov_b32_e32 v37, v24
	v_or_b32_e32 v38, 0x60, v2
	v_lshrrev_b32_e32 v3, 2, v38
	s_waitcnt lgkmcnt(0)
	v_add_f32_e32 v20, v20, v32
	s_nop 1
	v_mov_b32_dpp v32, v20 quad_perm:[2,3,0,1] row_mask:0xf bank_mask:0xf
	s_movk_i32 s0, 0x7f0
	v_and_or_b32 v3, v3, s0, v168
	v_cmp_gt_i32_e64 s[0:1], s91, v38
	s_waitcnt lgkmcnt(0)
	v_add_f32_e32 v20, v20, v32
	s_nop 1
	v_mov_b32_dpp v32, v20 row_half_mirror row_mask:0xf bank_mask:0xf
	s_waitcnt lgkmcnt(0)
	v_add_f32_e32 v20, v20, v32
	s_nop 1
	v_mov_b32_dpp v32, v20 row_mirror row_mask:0xf bank_mask:0xf
	s_waitcnt lgkmcnt(0)
	v_add_f32_e32 v20, v20, v32
	v_fmamk_f32 v20, v20, 0x3c800000, v197
	v_cmp_gt_f32_e32 vcc, s92, v20
	v_mul_f32_e32 v32, 0x4b800000, v20
	s_nop 0
	v_cndmask_b32_e32 v20, v20, v32, vcc
	v_rsq_f32_e32 v20, v20
	s_nop 0
	v_mul_f32_e32 v32, 0x45800000, v20
	v_cndmask_b32_e32 v20, v20, v32, vcc
	v_pk_mul_f32 v[36:37], v[20:21], v[36:37] op_sel_hi:[0,1]
	v_pk_mul_f32 v[42:43], v[138:139], v[36:37]
	v_pk_mul_f32 v[36:37], v[20:21], v[40:41] op_sel_hi:[0,1]
	v_pk_mul_f32 v[40:41], v[136:137], v[36:37]
	v_lshlrev_b32_e32 v36, 2, v3
	v_mov_b32_e32 v3, v42
	v_mov_b32_e32 v45, v43
	v_mov_b32_e32 v46, v41
	v_mov_b32_e32 v48, v40
	s_and_saveexec_b64 s[10:11], s[0:1]
	s_cbranch_execz .LBB0_553
	v_mov_b32_e32 v37, v1
	v_lshl_add_u64 v[44:45], s[6:7], 0, v[36:37]
	global_load_dword v20, v[44:45], off
	v_add_co_u32_e32 v44, vcc, 0x2000, v44
	v_lshlrev_b32_e32 v3, 4, v38
	s_movk_i32 s12, 0x2c0
	v_addc_co_u32_e32 v45, vcc, 0, v45, vcc
	v_and_or_b32 v3, v3, s12, v168
	global_load_dword v24, v[44:45], off
	v_lshlrev_b32_e32 v44, 2, v3
	v_mov_b32_e32 v45, v1
	v_lshl_add_u64 v[44:45], s[6:7], 0, v[44:45]
	global_load_dword v49, v[44:45], off
	v_add_co_u32_e32 v44, vcc, 0x2000, v44
	s_waitcnt vmcnt(0) lgkmcnt(0)
	v_pk_mul_f32 v[50:51], v[42:43], v[20:21] op_sel_hi:[1,0]
	v_addc_co_u32_e32 v45, vcc, 0, v45, vcc
	global_load_dword v48, v[44:45], off
	v_pk_mul_f32 v[52:53], v[42:43], v[24:25] op_sel:[1,0] op_sel_hi:[0,0]
	v_pk_fma_f32 v[44:45], v[42:43], v[20:21], v[52:53] op_sel_hi:[1,0,1]
	v_sub_f32_e32 v3, v50, v52
	v_mul_f32_e32 v20, v41, v49
	v_mov_b32_e32 v54, v49
	s_waitcnt vmcnt(0) lgkmcnt(0)
	v_pk_fma_f32 v[46:47], v[40:41], v[48:49], v[20:21] op_sel_hi:[1,1,0] neg_lo:[1,0,0] neg_hi:[1,0,0]
	v_mov_b32_e32 v55, v48
	v_mul_f32_e32 v20, v41, v48
	v_pk_fma_f32 v[48:49], v[40:41], v[54:55], v[20:21] op_sel_hi:[1,1,0]

; __device__ __forceinline__ void inproj_tile(const Params& p, char* smem, int l, int mt, int nt) {
;     ...
;           float ss = 0.f;
; #pragma unroll
;           for (int n = 0; n < 4; ++n) ss += acc[m][n][j] * acc[m][n][j];
;           ss += __shfl_xor(ss, 1); ss += __shfl_xor(ss, 2); ss += __shfl_xor(ss, 4); ss += __shfl_xor(ss, 8);
;           float rstd = rsqrtf(ss * (1.f / 64.f) + EPSF);
;           int row = rowbase + m * 16 + fq * 4 + j;
;           float v[4];
; #pragma unroll
;           for (int n = 0; n < 4; ++n) v[n] = acc[m][n][j] * rstd * w4[n];
;           bool lat = row < MLAT;
;           float rv[4] = {v[0], v[1], v[2], v[3]};
;           if (lat) {
;             int t = row & 8191, pr = t >> 6, pc = t & 63;
;             float c0 = rope[pr * 16 + fr], s0 = rope[2048 + pr * 16 + fr];
;             float c1 = rope[pc * 16 + fr], s1 = rope[2048 + pc * 16 + fr];
;             rv[0] = v[0] * c0 - v[1] * s0; rv[1] = v[1] * c0 + v[0] * s0;
;             rv[2] = v[2] * c1 - v[3] * s1; rv[3] = v[3] * c1 + v[2] * s1;
.LBB0_561:
	s_or_b64 exec, exec, s[0:1]
	v_mov_b32_e32 v28, v25
	v_pk_mul_f32 v[38:39], v[28:29], v[28:29]
	v_mov_b32_e32 v20, v33
	v_pk_mul_f32 v[32:33], v[20:21], v[20:21]
	v_add_f32_e32 v3, v38, v39
	v_add_f32_e32 v3, v33, v3
	v_add_f32_e32 v3, v32, v3
	s_nop 1
	v_mov_b32_dpp v24, v3 quad_perm:[1,0,3,2] row_mask:0xf bank_mask:0xf
	s_waitcnt lgkmcnt(0)
	v_add_f32_e32 v3, v3, v24
	s_nop 1
	v_mov_b32_dpp v24, v3 quad_perm:[2,3,0,1] row_mask:0xf bank_mask:0xf
	s_waitcnt lgkmcnt(0)
	v_add_f32_e32 v3, v3, v24
	s_nop 1
	v_mov_b32_dpp v24, v3 row_half_mirror row_mask:0xf bank_mask:0xf
	s_waitcnt lgkmcnt(0)
	v_add_f32_e32 v3, v3, v24
	s_nop 1
	v_mov_b32_dpp v24, v3 row_mirror row_mask:0xf bank_mask:0xf
	s_waitcnt lgkmcnt(0)
	v_add_f32_e32 v3, v3, v24
	v_fmamk_f32 v3, v3, 0x3c800000, v197
	v_cmp_gt_f32_e32 vcc, s92, v3
	v_mul_f32_e32 v24, 0x4b800000, v3
	s_nop 0
	v_cndmask_b32_e32 v3, v3, v24, vcc
	v_rsq_f32_e32 v3, v3
	s_nop 0
	v_mul_f32_e32 v24, 0x45800000, v3
	v_cndmask_b32_e32 v32, v3, v24, vcc
	v_mov_b32_e32 v24, v29
	v_pk_mul_f32 v[24:25], v[32:33], v[24:25] op_sel_hi:[0,1]
	v_pk_mul_f32 v[20:21], v[32:33], v[20:21] op_sel_hi:[0,1]
	v_pk_mul_f32 v[28:29], v[138:139], v[24:25]
	v_pk_mul_f32 v[20:21], v[136:137], v[20:21]
	v_or_b32_e32 v24, 0x61, v2
	v_cmp_gt_i32_e64 s[0:1], s91, v24
	v_mov_b32_e32 v3, v28
	v_mov_b32_e32 v33, v29
	v_mov_b32_e32 v38, v21
	v_mov_b32_e32 v40, v20
	s_and_saveexec_b64 s[10:11], s[0:1]
	s_cbranch_execz .LBB0_563
	v_lshlrev_b32_e32 v3, 4, v24
	s_movk_i32 s12, 0x2d0
	v_and_or_b32 v3, v3, s12, v168
	v_mov_b32_e32 v37, v1
	v_lshlrev_b32_e32 v40, 2, v3
	v_mov_b32_e32 v41, v1
	v_lshl_add_u64 v[32:33], s[6:7], 0, v[36:37]
	v_lshl_add_u64 v[40:41], s[6:7], 0, v[40:41]
	global_load_dword v38, v[32:33], off
	global_load_dword v43, v[40:41], off
	v_add_co_u32_e32 v32, vcc, 0x2000, v32
	s_waitcnt vmcnt(0) lgkmcnt(0)
	v_pk_mul_f32 v[44:45], v[28:29], v[38:39] op_sel_hi:[1,0]
	v_addc_co_u32_e32 v33, vcc, 0, v33, vcc
	global_load_dword v32, v[32:33], off
	v_add_co_u32_e32 v40, vcc, 0x2000, v40
	s_nop 1
	v_addc_co_u32_e32 v41, vcc, 0, v41, vcc
	global_load_dword v42, v[40:41], off
	v_mov_b32_e32 v40, v43
	s_waitcnt vmcnt(0) lgkmcnt(0)
	v_pk_mul_f32 v[46:47], v[28:29], v[32:33] op_sel:[1,0] op_sel_hi:[0,0]
	v_pk_fma_f32 v[32:33], v[28:29], v[38:39], v[46:47] op_sel_hi:[1,0,1]
	v_sub_f32_e32 v3, v44, v46
	v_mul_f32_e32 v32, v21, v43
	v_pk_fma_f32 v[38:39], v[20:21], v[42:43], v[32:33] op_sel_hi:[1,1,0] neg_lo:[1,0,0] neg_hi:[1,0,0]
	v_mov_b32_e32 v41, v42
	v_mul_f32_e32 v32, v21, v42
	v_pk_fma_f32 v[40:41], v[20:21], v[40:41], v[32:33] op_sel_hi:[1,1,0]

; __device__ __forceinline__ void inproj_tile(const Params& p, char* smem, int l, int mt, int nt) {
;     ...
;           float ss = 0.f;
; #pragma unroll
;           for (int n = 0; n < 4; ++n) ss += acc[m][n][j] * acc[m][n][j];
;           ss += __shfl_xor(ss, 1); ss += __shfl_xor(ss, 2); ss += __shfl_xor(ss, 4); ss += __shfl_xor(ss, 8);
;           float rstd = rsqrtf(ss * (1.f / 64.f) + EPSF);
;           int row = rowbase + m * 16 + fq * 4 + j;
;           float v[4];
; #pragma unroll
;           for (int n = 0; n < 4; ++n) v[n] = acc[m][n][j] * rstd * w4[n];
;           bool lat = row < MLAT;
;           float rv[4] = {v[0], v[1], v[2], v[3]};
;           if (lat) {
;             int t = row & 8191, pr = t >> 6, pc = t & 63;
;             float c0 = rope[pr * 16 + fr], s0 = rope[2048 + pr * 16 + fr];
;             float c1 = rope[pc * 16 + fr], s1 = rope[2048 + pc * 16 + fr];
;             rv[0] = v[0] * c0 - v[1] * s0; rv[1] = v[1] * c0 + v[0] * s0;
;             rv[2] = v[2] * c1 - v[3] * s1; rv[3] = v[3] * c1 + v[2] * s1;
.LBB0_571:
	s_or_b64 exec, exec, s[0:1]
	v_mov_b32_e32 v20, v26
	v_mov_b32_e32 v21, v30
	v_pk_mul_f32 v[20:21], v[20:21], v[20:21]
	v_mov_b32_e32 v24, v34
	v_mov_b32_e32 v25, v22
	v_pk_mul_f32 v[28:29], v[24:25], v[24:25]
	v_add_f32_e32 v3, v20, v21
	v_add_f32_e32 v3, v29, v3
	v_add_f32_e32 v3, v28, v3
	s_nop 1
	v_mov_b32_dpp v20, v3 quad_perm:[1,0,3,2] row_mask:0xf bank_mask:0xf
	v_mov_b32_e32 v28, v30
	v_mov_b32_e32 v29, v26
	s_waitcnt lgkmcnt(0)
	v_add_f32_e32 v3, v3, v20
	s_nop 1
	v_mov_b32_dpp v20, v3 quad_perm:[2,3,0,1] row_mask:0xf bank_mask:0xf
	s_waitcnt lgkmcnt(0)
	v_add_f32_e32 v3, v3, v20
	s_nop 1
	v_mov_b32_dpp v20, v3 row_half_mirror row_mask:0xf bank_mask:0xf
	s_waitcnt lgkmcnt(0)
	v_add_f32_e32 v3, v3, v20
	s_nop 1
	v_mov_b32_dpp v20, v3 row_mirror row_mask:0xf bank_mask:0xf
	s_waitcnt lgkmcnt(0)
	v_add_f32_e32 v3, v3, v20
	v_fmamk_f32 v3, v3, 0x3c800000, v197
	v_cmp_gt_f32_e32 vcc, s92, v3
	v_mul_f32_e32 v20, 0x4b800000, v3
	s_nop 0
	v_cndmask_b32_e32 v3, v3, v20, vcc
	v_rsq_f32_e32 v3, v3
	s_nop 0
	v_mul_f32_e32 v20, 0x45800000, v3
	v_cndmask_b32_e32 v20, v3, v20, vcc
	v_pk_mul_f32 v[28:29], v[20:21], v[28:29] op_sel_hi:[0,1]
	v_pk_mul_f32 v[20:21], v[20:21], v[24:25] op_sel_hi:[0,1]
	v_pk_mul_f32 v[28:29], v[138:139], v[28:29]
	v_pk_mul_f32 v[20:21], v[136:137], v[20:21]
	v_or_b32_e32 v24, 0x62, v2
	v_cmp_gt_i32_e64 s[0:1], s91, v24
	v_mov_b32_e32 v3, v28
	v_mov_b32_e32 v33, v29
	v_mov_b32_e32 v38, v21
	v_mov_b32_e32 v40, v20
	s_and_saveexec_b64 s[10:11], s[0:1]
	s_cbranch_execz .LBB0_573
	v_mov_b32_e32 v37, v1
	v_lshl_add_u64 v[32:33], s[6:7], 0, v[36:37]
	global_load_dword v22, v[32:33], off
	v_add_co_u32_e32 v32, vcc, 0x2000, v32
	v_lshlrev_b32_e32 v3, 4, v24
	s_movk_i32 s12, 0x2e0
	v_addc_co_u32_e32 v33, vcc, 0, v33, vcc
	v_and_or_b32 v3, v3, s12, v168
	global_load_dword v26, v[32:33], off
	v_lshlrev_b32_e32 v32, 2, v3
	v_mov_b32_e32 v33, v1
	v_lshl_add_u64 v[32:33], s[6:7], 0, v[32:33]
	global_load_dword v41, v[32:33], off
	v_add_co_u32_e32 v32, vcc, 0x2000, v32
	s_waitcnt vmcnt(0) lgkmcnt(0)
	v_pk_mul_f32 v[42:43], v[28:29], v[22:23] op_sel_hi:[1,0]
	v_addc_co_u32_e32 v33, vcc, 0, v33, vcc
	global_load_dword v40, v[32:33], off
	v_pk_mul_f32 v[44:45], v[28:29], v[26:27] op_sel:[1,0] op_sel_hi:[0,0]
	v_pk_fma_f32 v[32:33], v[28:29], v[22:23], v[44:45] op_sel_hi:[1,0,1]
	v_sub_f32_e32 v3, v42, v44
	v_mul_f32_e32 v22, v21, v41
	v_mov_b32_e32 v46, v41
	s_waitcnt vmcnt(0) lgkmcnt(0)
	v_pk_fma_f32 v[38:39], v[20:21], v[40:41], v[22:23] op_sel_hi:[1,1,0] neg_lo:[1,0,0] neg_hi:[1,0,0]
	v_mov_b32_e32 v47, v40
	v_mul_f32_e32 v22, v21, v40
	v_pk_fma_f32 v[40:41], v[20:21], v[46:47], v[22:23] op_sel_hi:[1,1,0]

; __device__ __forceinline__ void inproj_tile(const Params& p, char* smem, int l, int mt, int nt) {
;     ...
;           float ss = 0.f;
; #pragma unroll
;           for (int n = 0; n < 4; ++n) ss += acc[m][n][j] * acc[m][n][j];
;           ss += __shfl_xor(ss, 1); ss += __shfl_xor(ss, 2); ss += __shfl_xor(ss, 4); ss += __shfl_xor(ss, 8);
;           float rstd = rsqrtf(ss * (1.f / 64.f) + EPSF);
;           int row = rowbase + m * 16 + fq * 4 + j;
;           float v[4];
; #pragma unroll
;           for (int n = 0; n < 4; ++n) v[n] = acc[m][n][j] * rstd * w4[n];
;           bool lat = row < MLAT;
;           float rv[4] = {v[0], v[1], v[2], v[3]};
;           if (lat) {
;             int t = row & 8191, pr = t >> 6, pc = t & 63;
;             float c0 = rope[pr * 16 + fr], s0 = rope[2048 + pr * 16 + fr];
;             float c1 = rope[pc * 16 + fr], s1 = rope[2048 + pc * 16 + fr];
;             rv[0] = v[0] * c0 - v[1] * s0; rv[1] = v[1] * c0 + v[0] * s0;
;             rv[2] = v[2] * c1 - v[3] * s1; rv[3] = v[3] * c1 + v[2] * s1;
.LBB0_581:
	s_or_b64 exec, exec, s[0:1]
	v_mov_b32_e32 v30, v27
	v_pk_mul_f32 v[20:21], v[30:31], v[30:31]
	v_mov_b32_e32 v22, v35
	v_pk_mul_f32 v[24:25], v[22:23], v[22:23]
	v_add_f32_e32 v3, v20, v21
	v_add_f32_e32 v3, v25, v3
	v_add_f32_e32 v3, v24, v3
	s_nop 1
	v_mov_b32_dpp v20, v3 quad_perm:[1,0,3,2] row_mask:0xf bank_mask:0xf
	v_mov_b32_e32 v26, v31
	s_waitcnt lgkmcnt(0)
	v_add_f32_e32 v3, v3, v20
	s_nop 1
	v_mov_b32_dpp v20, v3 quad_perm:[2,3,0,1] row_mask:0xf bank_mask:0xf
	s_waitcnt lgkmcnt(0)
	v_add_f32_e32 v3, v3, v20
	s_nop 1
	v_mov_b32_dpp v20, v3 row_half_mirror row_mask:0xf bank_mask:0xf
	s_waitcnt lgkmcnt(0)
	v_add_f32_e32 v3, v3, v20
	s_nop 1
	v_mov_b32_dpp v20, v3 row_mirror row_mask:0xf bank_mask:0xf
	s_waitcnt lgkmcnt(0)
	v_add_f32_e32 v3, v3, v20
	v_fmamk_f32 v3, v3, 0x3c800000, v197
	v_cmp_gt_f32_e32 vcc, s92, v3
	v_mul_f32_e32 v20, 0x4b800000, v3
	s_nop 0
	v_cndmask_b32_e32 v3, v3, v20, vcc
	v_rsq_f32_e32 v3, v3
	s_nop 0
	v_mul_f32_e32 v20, 0x45800000, v3
	v_cndmask_b32_e32 v20, v3, v20, vcc
	v_pk_mul_f32 v[24:25], v[20:21], v[26:27] op_sel_hi:[0,1]
	v_pk_mul_f32 v[20:21], v[20:21], v[22:23] op_sel_hi:[0,1]
	v_pk_mul_f32 v[24:25], v[138:139], v[24:25]
	v_pk_mul_f32 v[20:21], v[136:137], v[20:21]
	v_or_b32_e32 v22, 0x63, v2
	v_cmp_gt_i32_e64 s[0:1], s91, v22
	v_mov_b32_e32 v3, v24
	v_mov_b32_e32 v27, v25
	v_mov_b32_e32 v28, v21
	v_mov_b32_e32 v30, v20
	s_and_saveexec_b64 s[10:11], s[0:1]
	s_cbranch_execz .LBB0_583
	v_lshlrev_b32_e32 v3, 4, v22
	s_movk_i32 s12, 0x2f0
	v_and_or_b32 v3, v3, s12, v168
	v_mov_b32_e32 v37, v1
	v_lshlrev_b32_e32 v30, 2, v3
	v_mov_b32_e32 v31, v1
	v_lshl_add_u64 v[26:27], s[6:7], 0, v[36:37]
	v_lshl_add_u64 v[30:31], s[6:7], 0, v[30:31]
	global_load_dword v28, v[26:27], off
	global_load_dword v33, v[30:31], off
	v_add_co_u32_e32 v26, vcc, 0x2000, v26
	s_waitcnt vmcnt(0) lgkmcnt(0)
	v_pk_mul_f32 v[34:35], v[24:25], v[28:29] op_sel_hi:[1,0]
	v_addc_co_u32_e32 v27, vcc, 0, v27, vcc
	global_load_dword v26, v[26:27], off
	v_add_co_u32_e32 v30, vcc, 0x2000, v30
	s_nop 1
	v_addc_co_u32_e32 v31, vcc, 0, v31, vcc
	global_load_dword v32, v[30:31], off
	v_mov_b32_e32 v30, v33
	s_waitcnt vmcnt(0) lgkmcnt(0)
	v_pk_mul_f32 v[36:37], v[24:25], v[26:27] op_sel:[1,0] op_sel_hi:[0,0]
	v_pk_fma_f32 v[26:27], v[24:25], v[28:29], v[36:37] op_sel_hi:[1,0,1]
	v_sub_f32_e32 v3, v34, v36
	v_mul_f32_e32 v26, v21, v33
	v_pk_fma_f32 v[28:29], v[20:21], v[32:33], v[26:27] op_sel_hi:[1,1,0] neg_lo:[1,0,0] neg_hi:[1,0,0]
	v_mov_b32_e32 v31, v32
	v_mul_f32_e32 v26, v21, v32
	v_pk_fma_f32 v[30:31], v[20:21], v[30:31], v[26:27] op_sel_hi:[1,1,0]

; __device__ __forceinline__ void inproj_tile(const Params& p, char* smem, int l, int mt, int nt) {
;     ...
;           float ss = 0.f;
; #pragma unroll
;           for (int n = 0; n < 4; ++n) ss += acc[m][n][j] * acc[m][n][j];
;           ss += __shfl_xor(ss, 1); ss += __shfl_xor(ss, 2); ss += __shfl_xor(ss, 4); ss += __shfl_xor(ss, 8);
;           float rstd = rsqrtf(ss * (1.f / 64.f) + EPSF);
;           int row = rowbase + m * 16 + fq * 4 + j;
;           float v[4];
; #pragma unroll
;           for (int n = 0; n < 4; ++n) v[n] = acc[m][n][j] * rstd * w4[n];
;           bool lat = row < MLAT;
;           float rv[4] = {v[0], v[1], v[2], v[3]};
;           if (lat) {
;             int t = row & 8191, pr = t >> 6, pc = t & 63;
;             float c0 = rope[pr * 16 + fr], s0 = rope[2048 + pr * 16 + fr];
;             float c1 = rope[pc * 16 + fr], s1 = rope[2048 + pc * 16 + fr];
;             rv[0] = v[0] * c0 - v[1] * s0; rv[1] = v[1] * c0 + v[0] * s0;
;             rv[2] = v[2] * c1 - v[3] * s1; rv[3] = v[3] * c1 + v[2] * s1;
.LBB0_591:
	s_or_b64 exec, exec, s[0:1]
	v_mov_b32_e32 v20, v8
	v_mov_b32_e32 v21, v12
	v_pk_mul_f32 v[20:21], v[20:21], v[20:21]
	v_mov_b32_e32 v24, v16
	v_mov_b32_e32 v25, v4
	v_pk_mul_f32 v[26:27], v[24:25], v[24:25]
	v_add_f32_e32 v4, v20, v21
	v_add_f32_e32 v4, v27, v4
	v_add_f32_e32 v4, v26, v4
	s_nop 1
	v_mov_b32_dpp v16, v4 quad_perm:[1,0,3,2] row_mask:0xf bank_mask:0xf
	v_mov_b32_e32 v20, v12
	v_mov_b32_e32 v21, v8
	v_or_b32_e32 v22, 0x70, v2
	v_lshrrev_b32_e32 v3, 2, v22
	s_waitcnt lgkmcnt(0)
	v_add_f32_e32 v4, v4, v16
	s_nop 1
	v_mov_b32_dpp v16, v4 quad_perm:[2,3,0,1] row_mask:0xf bank_mask:0xf
	s_movk_i32 s0, 0x7f0
	v_and_or_b32 v3, v3, s0, v168
	v_cmp_gt_i32_e64 s[0:1], s91, v22
	s_waitcnt lgkmcnt(0)
	v_add_f32_e32 v4, v4, v16
	s_nop 1
	v_mov_b32_dpp v16, v4 row_half_mirror row_mask:0xf bank_mask:0xf
	s_waitcnt lgkmcnt(0)
	v_add_f32_e32 v4, v4, v16
	s_nop 1
	v_mov_b32_dpp v16, v4 row_mirror row_mask:0xf bank_mask:0xf
	s_waitcnt lgkmcnt(0)
	v_add_f32_e32 v4, v4, v16
	v_fmamk_f32 v4, v4, 0x3c800000, v197
	v_cmp_gt_f32_e32 vcc, s92, v4
	v_mul_f32_e32 v16, 0x4b800000, v4
	s_nop 0
	v_cndmask_b32_e32 v4, v4, v16, vcc
	v_rsq_f32_e32 v4, v4
	s_nop 0
	v_mul_f32_e32 v16, 0x45800000, v4
	v_cndmask_b32_e32 v4, v4, v16, vcc
	v_pk_mul_f32 v[20:21], v[4:5], v[20:21] op_sel_hi:[0,1]
	v_pk_mul_f32 v[26:27], v[138:139], v[20:21]
	v_pk_mul_f32 v[20:21], v[4:5], v[24:25] op_sel_hi:[0,1]
	v_pk_mul_f32 v[24:25], v[136:137], v[20:21]
	v_lshlrev_b32_e32 v20, 2, v3
	v_mov_b32_e32 v3, v26
	v_mov_b32_e32 v29, v27
	v_mov_b32_e32 v30, v25
	v_mov_b32_e32 v32, v24
	s_and_saveexec_b64 s[10:11], s[0:1]
	s_cbranch_execz .LBB0_593
	v_mov_b32_e32 v21, v1
	v_lshl_add_u64 v[28:29], s[6:7], 0, v[20:21]
	global_load_dword v4, v[28:29], off
	v_add_co_u32_e32 v28, vcc, 0x2000, v28
	v_lshlrev_b32_e32 v3, 4, v22
	s_movk_i32 s12, 0x3c0
	v_addc_co_u32_e32 v29, vcc, 0, v29, vcc
	v_and_or_b32 v3, v3, s12, v168
	global_load_dword v8, v[28:29], off
	v_lshlrev_b32_e32 v28, 2, v3
	v_mov_b32_e32 v29, v1
	v_lshl_add_u64 v[28:29], s[6:7], 0, v[28:29]
	global_load_dword v33, v[28:29], off
	v_add_co_u32_e32 v28, vcc, 0x2000, v28
	s_waitcnt vmcnt(0) lgkmcnt(0)
	v_pk_mul_f32 v[34:35], v[26:27], v[4:5] op_sel_hi:[1,0]
	v_addc_co_u32_e32 v29, vcc, 0, v29, vcc
	global_load_dword v32, v[28:29], off
	v_pk_mul_f32 v[36:37], v[26:27], v[8:9] op_sel:[1,0] op_sel_hi:[0,0]
	v_pk_fma_f32 v[28:29], v[26:27], v[4:5], v[36:37] op_sel_hi:[1,0,1]
	v_sub_f32_e32 v3, v34, v36
	v_mul_f32_e32 v4, v25, v33
	v_mov_b32_e32 v38, v33
	s_waitcnt vmcnt(0) lgkmcnt(0)
	v_pk_fma_f32 v[30:31], v[24:25], v[32:33], v[4:5] op_sel_hi:[1,1,0] neg_lo:[1,0,0] neg_hi:[1,0,0]
	v_mov_b32_e32 v39, v32
	v_mul_f32_e32 v4, v25, v32
	v_pk_fma_f32 v[32:33], v[24:25], v[38:39], v[4:5] op_sel_hi:[1,1,0]

; __device__ __forceinline__ void inproj_tile(const Params& p, char* smem, int l, int mt, int nt) {
;     ...
;           float ss = 0.f;
; #pragma unroll
;           for (int n = 0; n < 4; ++n) ss += acc[m][n][j] * acc[m][n][j];
;           ss += __shfl_xor(ss, 1); ss += __shfl_xor(ss, 2); ss += __shfl_xor(ss, 4); ss += __shfl_xor(ss, 8);
;           float rstd = rsqrtf(ss * (1.f / 64.f) + EPSF);
;           int row = rowbase + m * 16 + fq * 4 + j;
;           float v[4];
; #pragma unroll
;           for (int n = 0; n < 4; ++n) v[n] = acc[m][n][j] * rstd * w4[n];
;           bool lat = row < MLAT;
;           float rv[4] = {v[0], v[1], v[2], v[3]};
;           if (lat) {
;             int t = row & 8191, pr = t >> 6, pc = t & 63;
;             float c0 = rope[pr * 16 + fr], s0 = rope[2048 + pr * 16 + fr];
;             float c1 = rope[pc * 16 + fr], s1 = rope[2048 + pc * 16 + fr];
;             rv[0] = v[0] * c0 - v[1] * s0; rv[1] = v[1] * c0 + v[0] * s0;
;             rv[2] = v[2] * c1 - v[3] * s1; rv[3] = v[3] * c1 + v[2] * s1;
.LBB0_601:
	s_or_b64 exec, exec, s[0:1]
	v_mov_b32_e32 v12, v9
	v_pk_mul_f32 v[22:23], v[12:13], v[12:13]
	v_mov_b32_e32 v4, v17
	v_pk_mul_f32 v[16:17], v[4:5], v[4:5]
	v_add_f32_e32 v3, v22, v23
	v_add_f32_e32 v3, v17, v3
	v_add_f32_e32 v3, v16, v3
	s_nop 1
	v_mov_b32_dpp v8, v3 quad_perm:[1,0,3,2] row_mask:0xf bank_mask:0xf
	s_waitcnt lgkmcnt(0)
	v_add_f32_e32 v3, v3, v8
	s_nop 1
	v_mov_b32_dpp v8, v3 quad_perm:[2,3,0,1] row_mask:0xf bank_mask:0xf
	s_waitcnt lgkmcnt(0)
	v_add_f32_e32 v3, v3, v8
	s_nop 1
	v_mov_b32_dpp v8, v3 row_half_mirror row_mask:0xf bank_mask:0xf
	s_waitcnt lgkmcnt(0)
	v_add_f32_e32 v3, v3, v8
	s_nop 1
	v_mov_b32_dpp v8, v3 row_mirror row_mask:0xf bank_mask:0xf
	s_waitcnt lgkmcnt(0)
	v_add_f32_e32 v3, v3, v8
	v_fmamk_f32 v3, v3, 0x3c800000, v197
	v_cmp_gt_f32_e32 vcc, s92, v3
	v_mul_f32_e32 v8, 0x4b800000, v3
	s_nop 0
	v_cndmask_b32_e32 v3, v3, v8, vcc
	v_rsq_f32_e32 v3, v3
	s_nop 0
	v_mul_f32_e32 v8, 0x45800000, v3
	v_cndmask_b32_e32 v16, v3, v8, vcc
	v_mov_b32_e32 v8, v13
	v_pk_mul_f32 v[8:9], v[16:17], v[8:9] op_sel_hi:[0,1]
	v_pk_mul_f32 v[4:5], v[16:17], v[4:5] op_sel_hi:[0,1]
	v_pk_mul_f32 v[12:13], v[138:139], v[8:9]
	v_pk_mul_f32 v[4:5], v[136:137], v[4:5]
	v_or_b32_e32 v8, 0x71, v2
	v_cmp_gt_i32_e64 s[0:1], s91, v8
	v_mov_b32_e32 v3, v12
	v_mov_b32_e32 v17, v13
	v_mov_b32_e32 v22, v5
	v_mov_b32_e32 v24, v4
	s_and_saveexec_b64 s[10:11], s[0:1]
	s_cbranch_execz .LBB0_603
	v_lshlrev_b32_e32 v3, 4, v8
	s_movk_i32 s12, 0x3d0
	v_and_or_b32 v3, v3, s12, v168
	v_mov_b32_e32 v21, v1
	v_lshlrev_b32_e32 v24, 2, v3
	v_mov_b32_e32 v25, v1
	v_lshl_add_u64 v[16:17], s[6:7], 0, v[20:21]
	v_lshl_add_u64 v[24:25], s[6:7], 0, v[24:25]
	global_load_dword v22, v[16:17], off
	global_load_dword v27, v[24:25], off
	v_add_co_u32_e32 v16, vcc, 0x2000, v16
	s_waitcnt vmcnt(0) lgkmcnt(0)
	v_pk_mul_f32 v[28:29], v[12:13], v[22:23] op_sel_hi:[1,0]
	v_addc_co_u32_e32 v17, vcc, 0, v17, vcc
	global_load_dword v16, v[16:17], off
	v_add_co_u32_e32 v24, vcc, 0x2000, v24
	s_nop 1
	v_addc_co_u32_e32 v25, vcc, 0, v25, vcc
	global_load_dword v26, v[24:25], off
	v_mov_b32_e32 v24, v27
	s_waitcnt vmcnt(0) lgkmcnt(0)
	v_pk_mul_f32 v[30:31], v[12:13], v[16:17] op_sel:[1,0] op_sel_hi:[0,0]
	v_pk_fma_f32 v[16:17], v[12:13], v[22:23], v[30:31] op_sel_hi:[1,0,1]
	v_sub_f32_e32 v3, v28, v30
	v_mul_f32_e32 v16, v5, v27
	v_pk_fma_f32 v[22:23], v[4:5], v[26:27], v[16:17] op_sel_hi:[1,1,0] neg_lo:[1,0,0] neg_hi:[1,0,0]
	v_mov_b32_e32 v25, v26
	v_mul_f32_e32 v16, v5, v26
	v_pk_fma_f32 v[24:25], v[4:5], v[24:25], v[16:17] op_sel_hi:[1,1,0]

; __device__ __forceinline__ void inproj_tile(const Params& p, char* smem, int l, int mt, int nt) {
;     ...
;           float ss = 0.f;
; #pragma unroll
;           for (int n = 0; n < 4; ++n) ss += acc[m][n][j] * acc[m][n][j];
;           ss += __shfl_xor(ss, 1); ss += __shfl_xor(ss, 2); ss += __shfl_xor(ss, 4); ss += __shfl_xor(ss, 8);
;           float rstd = rsqrtf(ss * (1.f / 64.f) + EPSF);
;           int row = rowbase + m * 16 + fq * 4 + j;
;           float v[4];
; #pragma unroll
;           for (int n = 0; n < 4; ++n) v[n] = acc[m][n][j] * rstd * w4[n];
;           bool lat = row < MLAT;
;           float rv[4] = {v[0], v[1], v[2], v[3]};
;           if (lat) {
;             int t = row & 8191, pr = t >> 6, pc = t & 63;
;             float c0 = rope[pr * 16 + fr], s0 = rope[2048 + pr * 16 + fr];
;             float c1 = rope[pc * 16 + fr], s1 = rope[2048 + pc * 16 + fr];
;             rv[0] = v[0] * c0 - v[1] * s0; rv[1] = v[1] * c0 + v[0] * s0;
;             rv[2] = v[2] * c1 - v[3] * s1; rv[3] = v[3] * c1 + v[2] * s1;
.LBB0_611:
	s_or_b64 exec, exec, s[0:1]
	v_mov_b32_e32 v4, v10
	v_mov_b32_e32 v5, v14
	v_pk_mul_f32 v[4:5], v[4:5], v[4:5]
	v_mov_b32_e32 v8, v18
	v_mov_b32_e32 v9, v6
	v_pk_mul_f32 v[12:13], v[8:9], v[8:9]
	v_add_f32_e32 v3, v4, v5
	v_add_f32_e32 v3, v13, v3
	v_add_f32_e32 v3, v12, v3
	s_nop 1
	v_mov_b32_dpp v4, v3 quad_perm:[1,0,3,2] row_mask:0xf bank_mask:0xf
	v_mov_b32_e32 v12, v14
	v_mov_b32_e32 v13, v10
	s_waitcnt lgkmcnt(0)
	v_add_f32_e32 v3, v3, v4
	s_nop 1
	v_mov_b32_dpp v4, v3 quad_perm:[2,3,0,1] row_mask:0xf bank_mask:0xf
	s_waitcnt lgkmcnt(0)
	v_add_f32_e32 v3, v3, v4
	s_nop 1
	v_mov_b32_dpp v4, v3 row_half_mirror row_mask:0xf bank_mask:0xf
	s_waitcnt lgkmcnt(0)
	v_add_f32_e32 v3, v3, v4
	s_nop 1
	v_mov_b32_dpp v4, v3 row_mirror row_mask:0xf bank_mask:0xf
	s_waitcnt lgkmcnt(0)
	v_add_f32_e32 v3, v3, v4
	v_fmamk_f32 v3, v3, 0x3c800000, v197
	v_cmp_gt_f32_e32 vcc, s92, v3
	v_mul_f32_e32 v4, 0x4b800000, v3
	s_nop 0
	v_cndmask_b32_e32 v3, v3, v4, vcc
	v_rsq_f32_e32 v3, v3
	s_nop 0
	v_mul_f32_e32 v4, 0x45800000, v3
	v_cndmask_b32_e32 v4, v3, v4, vcc
	v_pk_mul_f32 v[12:13], v[4:5], v[12:13] op_sel_hi:[0,1]
	v_pk_mul_f32 v[4:5], v[4:5], v[8:9] op_sel_hi:[0,1]
	v_pk_mul_f32 v[12:13], v[138:139], v[12:13]
	v_pk_mul_f32 v[4:5], v[136:137], v[4:5]
	v_or_b32_e32 v8, 0x72, v2
	v_cmp_gt_i32_e64 s[0:1], s91, v8
	v_mov_b32_e32 v3, v12
	v_mov_b32_e32 v17, v13
	v_mov_b32_e32 v22, v5
	v_mov_b32_e32 v24, v4
	s_and_saveexec_b64 s[10:11], s[0:1]
	s_cbranch_execz .LBB0_613
	v_mov_b32_e32 v21, v1
	v_lshl_add_u64 v[16:17], s[6:7], 0, v[20:21]
	global_load_dword v6, v[16:17], off
	v_add_co_u32_e32 v16, vcc, 0x2000, v16
	v_lshlrev_b32_e32 v3, 4, v8
	s_movk_i32 s12, 0x3e0
	v_addc_co_u32_e32 v17, vcc, 0, v17, vcc
	v_and_or_b32 v3, v3, s12, v168
	global_load_dword v10, v[16:17], off
	v_lshlrev_b32_e32 v16, 2, v3
	v_mov_b32_e32 v17, v1
	v_lshl_add_u64 v[16:17], s[6:7], 0, v[16:17]
	global_load_dword v25, v[16:17], off
	v_add_co_u32_e32 v16, vcc, 0x2000, v16
	s_waitcnt vmcnt(0) lgkmcnt(0)
	v_pk_mul_f32 v[26:27], v[12:13], v[6:7] op_sel_hi:[1,0]
	v_addc_co_u32_e32 v17, vcc, 0, v17, vcc
	global_load_dword v24, v[16:17], off
	v_pk_mul_f32 v[28:29], v[12:13], v[10:11] op_sel:[1,0] op_sel_hi:[0,0]
	v_pk_fma_f32 v[16:17], v[12:13], v[6:7], v[28:29] op_sel_hi:[1,0,1]
	v_sub_f32_e32 v3, v26, v28
	v_mul_f32_e32 v6, v5, v25
	v_mov_b32_e32 v30, v25
	s_waitcnt vmcnt(0) lgkmcnt(0)
	v_pk_fma_f32 v[22:23], v[4:5], v[24:25], v[6:7] op_sel_hi:[1,1,0] neg_lo:[1,0,0] neg_hi:[1,0,0]
	v_mov_b32_e32 v31, v24
	v_mul_f32_e32 v6, v5, v24
	v_pk_fma_f32 v[24:25], v[4:5], v[30:31], v[6:7] op_sel_hi:[1,1,0]

; __device__ __forceinline__ void inproj_tile(const Params& p, char* smem, int l, int mt, int nt) {
;     ...
;           float ss = 0.f;
; #pragma unroll
;           for (int n = 0; n < 4; ++n) ss += acc[m][n][j] * acc[m][n][j];
;           ss += __shfl_xor(ss, 1); ss += __shfl_xor(ss, 2); ss += __shfl_xor(ss, 4); ss += __shfl_xor(ss, 8);
;           float rstd = rsqrtf(ss * (1.f / 64.f) + EPSF);
;           int row = rowbase + m * 16 + fq * 4 + j;
;           float v[4];
; #pragma unroll
;           for (int n = 0; n < 4; ++n) v[n] = acc[m][n][j] * rstd * w4[n];
;           bool lat = row < MLAT;
;           float rv[4] = {v[0], v[1], v[2], v[3]};
;           if (lat) {
;             int t = row & 8191, pr = t >> 6, pc = t & 63;
;             float c0 = rope[pr * 16 + fr], s0 = rope[2048 + pr * 16 + fr];
;             float c1 = rope[pc * 16 + fr], s1 = rope[2048 + pc * 16 + fr];
;             rv[0] = v[0] * c0 - v[1] * s0; rv[1] = v[1] * c0 + v[0] * s0;
;             rv[2] = v[2] * c1 - v[3] * s1; rv[3] = v[3] * c1 + v[2] * s1;
.LBB0_621:
	s_or_b64 exec, exec, s[0:1]
	v_mov_b32_e32 v14, v11
	v_pk_mul_f32 v[4:5], v[14:15], v[14:15]
	v_mov_b32_e32 v6, v19
	v_pk_mul_f32 v[8:9], v[6:7], v[6:7]
	v_add_f32_e32 v3, v4, v5
	v_add_f32_e32 v3, v9, v3
	v_add_f32_e32 v3, v8, v3
	s_nop 1
	v_mov_b32_dpp v4, v3 quad_perm:[1,0,3,2] row_mask:0xf bank_mask:0xf
	v_mov_b32_e32 v10, v15
	v_or_b32_e32 v2, 0x73, v2
	v_cmp_gt_i32_e64 s[0:1], s91, v2
	s_waitcnt lgkmcnt(0)
	v_add_f32_e32 v3, v3, v4
	s_nop 1
	v_mov_b32_dpp v4, v3 quad_perm:[2,3,0,1] row_mask:0xf bank_mask:0xf
	s_waitcnt lgkmcnt(0)
	v_add_f32_e32 v3, v3, v4
	s_nop 1
	v_mov_b32_dpp v4, v3 row_half_mirror row_mask:0xf bank_mask:0xf
	s_waitcnt lgkmcnt(0)
	v_add_f32_e32 v3, v3, v4
	s_nop 1
	v_mov_b32_dpp v4, v3 row_mirror row_mask:0xf bank_mask:0xf
	s_waitcnt lgkmcnt(0)
	v_add_f32_e32 v3, v3, v4
	v_fmamk_f32 v3, v3, 0x3c800000, v197
	v_cmp_gt_f32_e32 vcc, s92, v3
	v_mul_f32_e32 v4, 0x4b800000, v3
	s_nop 0
	v_cndmask_b32_e32 v3, v3, v4, vcc
	v_rsq_f32_e32 v3, v3
	s_nop 0
	v_mul_f32_e32 v4, 0x45800000, v3
	v_cndmask_b32_e32 v4, v3, v4, vcc
	v_pk_mul_f32 v[8:9], v[4:5], v[10:11] op_sel_hi:[0,1]
	v_pk_mul_f32 v[4:5], v[4:5], v[6:7] op_sel_hi:[0,1]
	v_pk_mul_f32 v[8:9], v[138:139], v[8:9]
	v_pk_mul_f32 v[4:5], v[136:137], v[4:5]
	v_mov_b32_e32 v6, v8
	v_mov_b32_e32 v7, v9
	v_mov_b32_e32 v10, v5
	v_mov_b32_e32 v12, v4
	s_and_saveexec_b64 s[10:11], s[0:1]
	s_cbranch_execz .LBB0_623
	v_lshlrev_b32_e32 v3, 4, v2
	s_movk_i32 s12, 0x3f0
	v_and_or_b32 v3, v3, s12, v168
	v_mov_b32_e32 v21, v1
	v_lshlrev_b32_e32 v12, 2, v3
	v_mov_b32_e32 v13, v1
	v_lshl_add_u64 v[6:7], s[6:7], 0, v[20:21]
	v_lshl_add_u64 v[12:13], s[6:7], 0, v[12:13]
	global_load_dword v10, v[6:7], off
	global_load_dword v15, v[12:13], off
	v_add_co_u32_e32 v6, vcc, 0x2000, v6
	s_waitcnt vmcnt(0) lgkmcnt(0)
	v_pk_mul_f32 v[16:17], v[8:9], v[10:11] op_sel_hi:[1,0]
	v_addc_co_u32_e32 v7, vcc, 0, v7, vcc
	global_load_dword v6, v[6:7], off
	v_add_co_u32_e32 v12, vcc, 0x2000, v12
	s_nop 1
	v_addc_co_u32_e32 v13, vcc, 0, v13, vcc
	global_load_dword v14, v[12:13], off
	v_mov_b32_e32 v12, v15
	s_waitcnt vmcnt(0) lgkmcnt(0)
	v_pk_mul_f32 v[18:19], v[8:9], v[6:7] op_sel:[1,0] op_sel_hi:[0,0]
	v_pk_fma_f32 v[6:7], v[8:9], v[10:11], v[18:19] op_sel_hi:[1,0,1]
	v_mov_b32_e32 v13, v14
	v_mul_f32_e32 v6, v5, v15
	v_pk_fma_f32 v[10:11], v[4:5], v[14:15], v[6:7] op_sel_hi:[1,1,0] neg_lo:[1,0,0] neg_hi:[1,0,0]
	v_mul_f32_e32 v6, v5, v14
	v_pk_fma_f32 v[12:13], v[4:5], v[12:13], v[6:7] op_sel_hi:[1,1,0]
	v_sub_f32_e32 v6, v16, v18
